# softmax scale*log2e folded into q at the producers (mlaup/proj epilogues, before the bf16 rounding); dense loops use 4-byte v_sub (s - m) instead of 8-byte v_fmamk
# baseline (speedup 1.0000x reference)
; DI bf16_t* wsb(const Ctx& c, size_t off) { return (bf16_t*)(c.ws + off); }
; template <int N> DI void rmsnorm_inplace(float* v, const float* __restrict__ g) {
;   float s = 0.f;
; #pragma unroll
;   for (int i = 0; i < N; ++i) s += v[i] * v[i];
;   const float r = rsqrtf(s * (1.0f / N) + EPS);
; #pragma unroll
;   for (int i = 0; i < N; ++i) v[i] = v[i] * r * g[i];
; }
; DI void phase_proj(const Ctx& c, bool dummy_ss = false) {
;     ...
;       } else {
;         const bool isq = slot < 51;
;         rmsnorm_inplace<64>(v, inl(c, isq ? 18 : 19, 64));
;         bf16_t* dst = isq ? wsb(c, OFF_QC) + ((size_t)(seq * 8 + (slot - 43)) * S + pos) * 64
;                           : wsb(c, OFF_KC) + ((size_t)(seq * 2 + (slot - 51)) * S + pos) * 64;
;         asm volatile("" ::: "memory");
;         rope32(v, rope + (size_t)(pos >> 6) * 16);
;         store_bf16<32>(dst, v);
.LBB0_511:
	v_pk_mul_f32 v[132:133], v[66:67], v[66:67]
	v_pk_mul_f32 v[136:137], v[82:83], v[82:83]
	v_add_f32_e32 v130, v132, v133
	v_add_f32_e32 v130, v136, v130
	v_pk_mul_f32 v[138:139], v[84:85], v[84:85]
	v_add_f32_e32 v130, v137, v130
	v_add_f32_e32 v130, v138, v130
	v_pk_mul_f32 v[140:141], v[114:115], v[114:115]
	v_add_f32_e32 v130, v139, v130
	v_add_f32_e32 v130, v140, v130
	v_pk_mul_f32 v[142:143], v[68:69], v[68:69]
	v_add_f32_e32 v130, v141, v130
	v_add_f32_e32 v130, v142, v130
	v_pk_mul_f32 v[132:133], v[86:87], v[86:87]
	v_add_f32_e32 v130, v143, v130
	v_add_f32_e32 v130, v132, v130
	v_pk_mul_f32 v[136:137], v[88:89], v[88:89]
	v_add_f32_e32 v130, v133, v130
	v_add_f32_e32 v130, v136, v130
	v_pk_mul_f32 v[138:139], v[116:117], v[116:117]
	v_add_f32_e32 v130, v137, v130
	v_add_f32_e32 v130, v138, v130
	v_pk_mul_f32 v[140:141], v[70:71], v[70:71]
	v_add_f32_e32 v130, v139, v130
	v_add_f32_e32 v130, v140, v130
	v_pk_mul_f32 v[132:133], v[90:91], v[90:91]
	v_add_f32_e32 v130, v141, v130
	v_add_f32_e32 v130, v132, v130
	v_pk_mul_f32 v[136:137], v[92:93], v[92:93]
	v_add_f32_e32 v130, v133, v130
	v_add_f32_e32 v130, v136, v130
	v_pk_mul_f32 v[138:139], v[118:119], v[118:119]
	v_add_f32_e32 v130, v137, v130
	v_add_f32_e32 v130, v138, v130
	v_pk_mul_f32 v[140:141], v[72:73], v[72:73]
	v_add_f32_e32 v130, v139, v130
	v_add_f32_e32 v130, v140, v130
	v_pk_mul_f32 v[132:133], v[94:95], v[94:95]
	v_add_f32_e32 v130, v141, v130
	v_add_f32_e32 v130, v132, v130
	v_pk_mul_f32 v[136:137], v[96:97], v[96:97]
	v_add_f32_e32 v130, v133, v130
	v_add_f32_e32 v130, v136, v130
	v_pk_mul_f32 v[138:139], v[120:121], v[120:121]
	v_add_f32_e32 v130, v137, v130
	v_add_f32_e32 v130, v138, v130
	v_pk_mul_f32 v[140:141], v[74:75], v[74:75]
	v_add_f32_e32 v130, v139, v130
	v_add_f32_e32 v130, v140, v130
	v_pk_mul_f32 v[132:133], v[98:99], v[98:99]
	v_add_f32_e32 v130, v141, v130
	v_add_f32_e32 v130, v132, v130
	v_pk_mul_f32 v[136:137], v[100:101], v[100:101]
	v_add_f32_e32 v130, v133, v130
	v_add_f32_e32 v130, v136, v130
	v_pk_mul_f32 v[138:139], v[122:123], v[122:123]
	v_add_f32_e32 v130, v137, v130
	v_add_f32_e32 v130, v138, v130
	v_pk_mul_f32 v[140:141], v[76:77], v[76:77]
	v_add_f32_e32 v130, v139, v130
	v_add_f32_e32 v130, v140, v130
	v_pk_mul_f32 v[132:133], v[102:103], v[102:103]
	v_add_f32_e32 v130, v141, v130
	v_add_f32_e32 v130, v132, v130
	v_pk_mul_f32 v[136:137], v[104:105], v[104:105]
	v_add_f32_e32 v130, v133, v130
	v_add_f32_e32 v130, v136, v130
	v_pk_mul_f32 v[138:139], v[124:125], v[124:125]
	v_add_f32_e32 v130, v137, v130
	v_add_f32_e32 v130, v138, v130
	v_pk_mul_f32 v[132:133], v[78:79], v[78:79]
	v_add_f32_e32 v130, v139, v130
	v_add_f32_e32 v130, v132, v130
	v_pk_mul_f32 v[136:137], v[106:107], v[106:107]
	v_add_f32_e32 v130, v133, v130
	v_add_f32_e32 v130, v136, v130
	v_pk_mul_f32 v[138:139], v[108:109], v[108:109]
	v_add_f32_e32 v130, v137, v130
	v_add_f32_e32 v130, v138, v130
	v_pk_mul_f32 v[132:133], v[126:127], v[126:127]
	v_add_f32_e32 v130, v139, v130
	v_add_f32_e32 v130, v132, v130
	v_pk_mul_f32 v[136:137], v[80:81], v[80:81]
	v_add_f32_e32 v130, v133, v130
	v_add_f32_e32 v130, v136, v130
	v_pk_mul_f32 v[138:139], v[110:111], v[110:111]
	v_add_f32_e32 v130, v137, v130
	v_add_f32_e32 v130, v138, v130
	v_pk_mul_f32 v[132:133], v[112:113], v[112:113]
	v_add_f32_e32 v130, v139, v130
	v_add_f32_e32 v130, v132, v130
	v_pk_mul_f32 v[136:137], v[128:129], v[128:129]
	v_add_f32_e32 v130, v133, v130
	v_add_f32_e32 v130, v136, v130
	v_add_f32_e32 v130, v137, v130
	v_fmamk_f32 v130, v130, 0x3c800000, v198
	s_cmp_lt_u32 s36, 51
	s_cselect_b32 s100, 0x3e38aa3b, 1.0
	s_mov_b32 s26, 0x800000
	v_mul_f32_e32 v132, 0x4b800000, v130
	v_cmp_gt_f32_e32 vcc, s26, v130
	v_readlane_b32 s26, v252, 7
	v_readlane_b32 s27, v252, 8
	v_cndmask_b32_e32 v130, v130, v132, vcc
	v_rsq_f32_e32 v130, v130
	v_lshlrev_b32_e32 v132, 1, v0
	v_and_b32_e32 v135, 0x7f80, v132
	s_add_u32 s4, s94, s4
	v_mul_f32_e32 v132, 0x45800000, v130
	v_cndmask_b32_e32 v130, v130, v132, vcc
	v_mul_f32_e32 v130, s100, v130
	v_pk_mul_f32 v[132:133], v[66:67], v[130:131] op_sel_hi:[1,0]
	s_addc_u32 s5, s95, s5
	s_waitcnt vmcnt(12)
	v_pk_mul_f32 v[136:137], v[132:133], v[58:59]
	v_pk_mul_f32 v[58:59], v[70:71], v[130:131] op_sel_hi:[1,0]
	s_lshl_b64 s[2:3], s[2:3], s20
	s_waitcnt vmcnt(8)
	v_pk_mul_f32 v[138:139], v[58:59], v[62:63]
	v_pk_mul_f32 v[58:59], v[82:83], v[130:131] op_sel_hi:[1,0]
	s_mov_b32 s69, s46
	v_pk_mul_f32 v[60:61], v[58:59], v[60:61]
	v_pk_mul_f32 v[58:59], v[90:91], v[130:131] op_sel_hi:[1,0]
	s_nop 0
	v_pk_mul_f32 v[140:141], v[58:59], v[64:65]
	v_pk_mul_f32 v[58:59], v[84:85], v[130:131] op_sel_hi:[1,0]
	s_nop 0
	v_pk_mul_f32 v[142:143], v[58:59], v[50:51]
	v_pk_mul_f32 v[50:51], v[92:93], v[130:131] op_sel_hi:[1,0]
	s_nop 0
	v_pk_mul_f32 v[144:145], v[50:51], v[54:55]
	v_pk_mul_f32 v[50:51], v[114:115], v[130:131] op_sel_hi:[1,0]
	s_nop 0
	v_pk_mul_f32 v[146:147], v[50:51], v[52:53]
	v_pk_mul_f32 v[50:51], v[118:119], v[130:131] op_sel_hi:[1,0]
	s_nop 0
	v_pk_mul_f32 v[148:149], v[50:51], v[56:57]
	v_pk_mul_f32 v[50:51], v[68:69], v[130:131] op_sel_hi:[1,0]
	s_nop 0
	v_pk_mul_f32 v[58:59], v[50:51], v[42:43]
	v_pk_mul_f32 v[42:43], v[72:73], v[130:131] op_sel_hi:[1,0]
	global_load_dwordx4 v[50:53], v135, s[26:27] offset:32
	v_pk_mul_f32 v[132:133], v[42:43], v[46:47]
	v_pk_mul_f32 v[42:43], v[86:87], v[130:131] op_sel_hi:[1,0]
	s_nop 0
	v_pk_mul_f32 v[62:63], v[42:43], v[44:45]
	global_load_dwordx4 v[44:47], v135, s[26:27]
	v_pk_mul_f32 v[42:43], v[94:95], v[130:131] op_sel_hi:[1,0]
	s_nop 0
	v_pk_mul_f32 v[64:65], v[42:43], v[48:49]
	v_pk_mul_f32 v[42:43], v[88:89], v[130:131] op_sel_hi:[1,0]
	s_nop 0
	v_pk_mul_f32 v[42:43], v[42:43], v[34:35]
	v_pk_mul_f32 v[34:35], v[96:97], v[130:131] op_sel_hi:[1,0]
	s_nop 0
	v_pk_mul_f32 v[54:55], v[34:35], v[38:39]
	v_pk_mul_f32 v[34:35], v[116:117], v[130:131] op_sel_hi:[1,0]
	s_waitcnt vmcnt(0)
; DI bf16_t* wsb(const Ctx& c, size_t off) { return (bf16_t*)(c.ws + off); }
; DI void rope32(float* v, const f32x2* __restrict__ tab  ) {
; #pragma unroll
;   for (int i = 0; i < 16; ++i) { const f32x2 cs = tab[i]; const float x1 = v[i], x2 = v[i + 16]; v[i] = x1 * cs.x - x2 * cs.y; v[i + 16] = x1 * cs.y + x2 * cs.x; }
; }
; DI void phase_proj(const Ctx& c, bool dummy_ss = false) {
;     ...
;       } else {
;         const bool isq = slot < 51;
;         rmsnorm_inplace<64>(v, inl(c, isq ? 18 : 19, 64));
;         bf16_t* dst = isq ? wsb(c, OFF_QC) + ((size_t)(seq * 8 + (slot - 43)) * S + pos) * 64
;                           : wsb(c, OFF_KC) + ((size_t)(seq * 2 + (slot - 51)) * S + pos) * 64;
;         asm volatile("" ::: "memory");
;         rope32(v, rope + (size_t)(pos >> 6) * 16);
;         store_bf16<32>(dst, v);
;         asm volatile("" ::: "memory");
;         rope32(v + 32, rope + (size_t)(pos & 63) * 16);
;         store_bf16<32>(dst + 32, v + 32);
	v_mov_b32_e32 v39, v46
	v_pk_mul_f32 v[34:35], v[34:35], v[36:37]
	v_pk_mul_f32 v[36:37], v[120:121], v[130:131] op_sel_hi:[1,0]
	v_mov_b32_e32 v46, v45
	v_pk_mul_f32 v[36:37], v[36:37], v[40:41]
	v_mov_b32_e32 v38, v44
	v_pk_mul_f32 v[40:41], v[138:139], v[46:47]
	s_nop 0
	v_pk_fma_f32 v[40:41], v[136:137], v[38:39], v[40:41] neg_lo:[0,0,1] neg_hi:[0,0,1]
	v_pk_mul_f32 v[38:39], v[138:139], v[38:39]
	s_nop 0
	v_pk_fma_f32 v[38:39], v[136:137], v[46:47], v[38:39]
	global_load_dwordx4 v[46:49], v135, s[26:27] offset:16
	global_load_dwordx4 v[136:139], v135, s[26:27] offset:48
	s_waitcnt vmcnt(1)
	v_mov_b32_e32 v45, v48
	v_mov_b32_e32 v48, v47
	v_mov_b32_e32 v44, v46
	v_pk_mul_f32 v[46:47], v[140:141], v[48:49]
	s_nop 0
	v_pk_fma_f32 v[46:47], v[60:61], v[44:45], v[46:47] neg_lo:[0,0,1] neg_hi:[0,0,1]
	v_pk_mul_f32 v[44:45], v[140:141], v[44:45]
	s_nop 0
	v_pk_fma_f32 v[44:45], v[60:61], v[48:49], v[44:45]
	v_mov_b32_e32 v49, v52
	v_mov_b32_e32 v52, v51
	v_mov_b32_e32 v48, v50
	v_pk_mul_f32 v[50:51], v[144:145], v[52:53]
	s_nop 0
	v_pk_fma_f32 v[50:51], v[142:143], v[48:49], v[50:51] neg_lo:[0,0,1] neg_hi:[0,0,1]
	v_pk_mul_f32 v[48:49], v[144:145], v[48:49]
	s_nop 0
	v_pk_fma_f32 v[48:49], v[142:143], v[52:53], v[48:49]
	s_waitcnt vmcnt(0)
	v_mov_b32_e32 v53, v138
	v_mov_b32_e32 v138, v137
	v_mov_b32_e32 v52, v136
	v_pk_mul_f32 v[56:57], v[148:149], v[138:139]
	s_nop 0
	v_pk_fma_f32 v[56:57], v[146:147], v[52:53], v[56:57] neg_lo:[0,0,1] neg_hi:[0,0,1]
	v_pk_mul_f32 v[52:53], v[148:149], v[52:53]
	s_nop 0
	v_pk_fma_f32 v[52:53], v[146:147], v[138:139], v[52:53]
	global_load_dwordx4 v[136:139], v135, s[26:27] offset:64
	s_waitcnt vmcnt(0)
	v_mov_b32_e32 v140, v136
	v_mov_b32_e32 v141, v138
	v_mov_b32_e32 v138, v137
	v_pk_mul_f32 v[60:61], v[132:133], v[138:139]
	v_pk_mul_f32 v[132:133], v[132:133], v[140:141]
	v_pk_fma_f32 v[60:61], v[58:59], v[140:141], v[60:61] neg_lo:[0,0,1] neg_hi:[0,0,1]
	v_pk_fma_f32 v[58:59], v[58:59], v[138:139], v[132:133]
	global_load_dwordx4 v[136:139], v135, s[26:27] offset:80
	s_waitcnt vmcnt(0)
	v_mov_b32_e32 v132, v136
	v_mov_b32_e32 v133, v138
	v_mov_b32_e32 v138, v137
	v_pk_mul_f32 v[136:137], v[64:65], v[138:139]
	v_pk_mul_f32 v[64:65], v[64:65], v[132:133]
	s_nop 0
	v_pk_fma_f32 v[64:65], v[62:63], v[138:139], v[64:65]
	v_pk_fma_f32 v[62:63], v[62:63], v[132:133], v[136:137] neg_lo:[0,0,1] neg_hi:[0,0,1]
	global_load_dwordx4 v[136:139], v135, s[26:27] offset:96
	s_waitcnt vmcnt(0)
	v_mov_b32_e32 v132, v136
	v_mov_b32_e32 v133, v138
	v_mov_b32_e32 v138, v137
	v_pk_mul_f32 v[140:141], v[54:55], v[138:139]
	v_pk_mul_f32 v[54:55], v[54:55], v[132:133]
	s_nop 0
	v_pk_fma_f32 v[54:55], v[42:43], v[138:139], v[54:55]
	global_load_dwordx4 v[136:139], v135, s[26:27] offset:112
	v_pk_fma_f32 v[42:43], v[42:43], v[132:133], v[140:141] neg_lo:[0,0,1] neg_hi:[0,0,1]
	s_waitcnt vmcnt(0)
	v_mov_b32_e32 v133, v138
	v_mov_b32_e32 v138, v137
	v_mov_b32_e32 v132, v136
	v_pk_mul_f32 v[136:137], v[36:37], v[138:139]
	v_pk_mul_f32 v[36:37], v[36:37], v[132:133]
	v_pk_fma_f32 v[136:137], v[34:35], v[132:133], v[136:137] neg_lo:[0,0,1] neg_hi:[0,0,1]
	v_lshl_add_u64 v[132:133], s[2:3], 0, v[0:1]
	v_lshlrev_b64 v[132:133], 7, v[132:133]
	v_lshl_add_u64 v[132:133], s[4:5], 0, v[132:133]
	v_pk_fma_f32 v[138:139], v[34:35], v[138:139], v[36:37]
	v_cvt_pk_bf16_f32 v34, v40, v41
	v_cvt_pk_bf16_f32 v35, v46, v47
	v_cvt_pk_bf16_f32 v36, v50, v51
	v_cvt_pk_bf16_f32 v37, v56, v57
	global_store_dwordx4 v[132:133], v[34:37], off
	s_mov_b64 s[2:3], 0
	s_nop 0
	v_cvt_pk_bf16_f32 v34, v60, v61
	v_cvt_pk_bf16_f32 v35, v62, v63
	v_cvt_pk_bf16_f32 v36, v42, v43
	v_cvt_pk_bf16_f32 v37, v136, v137
	global_store_dwordx4 v[132:133], v[34:37], off offset:16
	v_pk_mul_f32 v[136:137], v[74:75], v[130:131] op_sel_hi:[1,0]
	s_nop 0
	v_cvt_pk_bf16_f32 v34, v38, v39
	v_cvt_pk_bf16_f32 v35, v44, v45
	v_cvt_pk_bf16_f32 v36, v48, v49
	v_cvt_pk_bf16_f32 v37, v52, v53
	global_store_dwordx4 v[132:133], v[34:37], off offset:32
	v_pk_mul_f32 v[26:27], v[136:137], v[26:27]
	v_pk_mul_f32 v[136:137], v[78:79], v[130:131] op_sel_hi:[1,0]
	v_cvt_pk_bf16_f32 v34, v58, v59
	v_cvt_pk_bf16_f32 v35, v64, v65
	v_cvt_pk_bf16_f32 v36, v54, v55
	v_cvt_pk_bf16_f32 v37, v138, v139
	global_store_dwordx4 v[132:133], v[34:37], off offset:48
	v_pk_mul_f32 v[30:31], v[136:137], v[30:31]
	v_pk_mul_f32 v[136:137], v[98:99], v[130:131] op_sel_hi:[1,0]
	v_lshlrev_b32_e32 v34, 7, v134
	v_and_b32_e32 v62, 0x1f80, v34
	global_load_dwordx4 v[34:37], v62, s[26:27]
	global_load_dwordx4 v[38:41], v62, s[26:27] offset:16
	global_load_dwordx4 v[42:45], v62, s[26:27] offset:32
	global_load_dwordx4 v[46:49], v62, s[26:27] offset:48
	global_load_dwordx4 v[50:53], v62, s[26:27] offset:64
	global_load_dwordx4 v[54:57], v62, s[26:27] offset:80
	global_load_dwordx4 v[58:61], v62, s[26:27] offset:96
	s_nop 0
	global_load_dwordx4 v[62:65], v62, s[26:27] offset:112
	v_pk_mul_f32 v[28:29], v[136:137], v[28:29]
	v_pk_mul_f32 v[136:137], v[106:107], v[130:131] op_sel_hi:[1,0]
	s_movk_i32 s26, 0x280
	v_pk_mul_f32 v[32:33], v[136:137], v[32:33]
	v_pk_mul_f32 v[136:137], v[100:101], v[130:131] op_sel_hi:[1,0]
	s_nop 0
	v_pk_mul_f32 v[18:19], v[136:137], v[18:19]
	v_pk_mul_f32 v[136:137], v[108:109], v[130:131] op_sel_hi:[1,0]
	s_nop 0
	v_pk_mul_f32 v[22:23], v[136:137], v[22:23]
	v_pk_mul_f32 v[136:137], v[122:123], v[130:131] op_sel_hi:[1,0]
	s_nop 0
	v_pk_mul_f32 v[20:21], v[136:137], v[20:21]
	v_pk_mul_f32 v[136:137], v[126:127], v[130:131] op_sel_hi:[1,0]
	s_nop 0
	v_pk_mul_f32 v[24:25], v[136:137], v[24:25]
	v_pk_mul_f32 v[136:137], v[76:77], v[130:131] op_sel_hi:[1,0]
	s_nop 0
	v_pk_mul_f32 v[10:11], v[136:137], v[10:11]
	v_pk_mul_f32 v[136:137], v[80:81], v[130:131] op_sel_hi:[1,0]
	s_nop 0
	v_pk_mul_f32 v[14:15], v[136:137], v[14:15]
	v_pk_mul_f32 v[136:137], v[102:103], v[130:131] op_sel_hi:[1,0]
	s_nop 0
	v_pk_mul_f32 v[12:13], v[136:137], v[12:13]
	v_pk_mul_f32 v[136:137], v[110:111], v[130:131] op_sel_hi:[1,0]
	s_nop 0
	v_pk_mul_f32 v[16:17], v[136:137], v[16:17]
	v_pk_mul_f32 v[136:137], v[104:105], v[130:131] op_sel_hi:[1,0]
	s_nop 0
	v_pk_mul_f32 v[2:3], v[136:137], v[2:3]
	v_pk_mul_f32 v[136:137], v[112:113], v[130:131] op_sel_hi:[1,0]
	s_nop 0
	v_pk_mul_f32 v[6:7], v[136:137], v[6:7]
	v_pk_mul_f32 v[136:137], v[124:125], v[130:131] op_sel_hi:[1,0]
	s_nop 0
	v_pk_mul_f32 v[4:5], v[136:137], v[4:5]
	v_pk_mul_f32 v[136:137], v[128:129], v[130:131] op_sel_hi:[1,0]
	s_nop 0
	v_pk_mul_f32 v[8:9], v[136:137], v[8:9]
	s_waitcnt vmcnt(7)
; DI void rope32(float* v, const f32x2* __restrict__ tab  ) {
; #pragma unroll
;   for (int i = 0; i < 16; ++i) { const f32x2 cs = tab[i]; const float x1 = v[i], x2 = v[i + 16]; v[i] = x1 * cs.x - x2 * cs.y; v[i + 16] = x1 * cs.y + x2 * cs.x; }
; }
; DI void phase_proj(const Ctx& c, bool dummy_ss = false) {
;     ...
;         rope32(v, rope + (size_t)(pos >> 6) * 16);
;         store_bf16<32>(dst, v);
;         asm volatile("" ::: "memory");
;         rope32(v + 32, rope + (size_t)(pos & 63) * 16);
;         store_bf16<32>(dst + 32, v + 32);
	v_mov_b32_e32 v136, v34
	v_mov_b32_e32 v137, v36
	v_mov_b32_e32 v36, v35
	v_pk_mul_f32 v[34:35], v[30:31], v[36:37]
	v_pk_mul_f32 v[30:31], v[30:31], v[136:137]
	v_pk_fma_f32 v[34:35], v[26:27], v[136:137], v[34:35] neg_lo:[0,0,1] neg_hi:[0,0,1]
	v_pk_fma_f32 v[26:27], v[26:27], v[36:37], v[30:31]
	s_waitcnt vmcnt(6)
	v_mov_b32_e32 v31, v40
	v_mov_b32_e32 v40, v39
	v_mov_b32_e32 v30, v38
	v_pk_mul_f32 v[36:37], v[32:33], v[40:41]
	s_nop 0
	v_pk_fma_f32 v[36:37], v[28:29], v[30:31], v[36:37] neg_lo:[0,0,1] neg_hi:[0,0,1]
	v_pk_mul_f32 v[30:31], v[32:33], v[30:31]
	s_nop 0
	v_pk_fma_f32 v[28:29], v[28:29], v[40:41], v[30:31]
	s_waitcnt vmcnt(5)
	v_mov_b32_e32 v30, v42
	v_mov_b32_e32 v31, v44
	v_mov_b32_e32 v44, v43
	v_pk_mul_f32 v[32:33], v[22:23], v[44:45]
	v_pk_mul_f32 v[22:23], v[22:23], v[30:31]
	v_pk_fma_f32 v[32:33], v[18:19], v[30:31], v[32:33] neg_lo:[0,0,1] neg_hi:[0,0,1]
	v_pk_fma_f32 v[18:19], v[18:19], v[44:45], v[22:23]
	s_waitcnt vmcnt(4)
	v_mov_b32_e32 v23, v48
	v_mov_b32_e32 v48, v47
	v_mov_b32_e32 v22, v46
	v_pk_mul_f32 v[30:31], v[24:25], v[48:49]
	s_nop 0
	v_pk_fma_f32 v[30:31], v[20:21], v[22:23], v[30:31] neg_lo:[0,0,1] neg_hi:[0,0,1]
	v_pk_mul_f32 v[22:23], v[24:25], v[22:23]
	s_nop 0
	v_pk_fma_f32 v[20:21], v[20:21], v[48:49], v[22:23]
	s_waitcnt vmcnt(3)
	v_mov_b32_e32 v22, v50
	v_mov_b32_e32 v23, v52
	v_mov_b32_e32 v52, v51
	v_pk_mul_f32 v[24:25], v[14:15], v[52:53]
	v_pk_mul_f32 v[14:15], v[14:15], v[22:23]
	v_pk_fma_f32 v[24:25], v[10:11], v[22:23], v[24:25] neg_lo:[0,0,1] neg_hi:[0,0,1]
	v_pk_fma_f32 v[10:11], v[10:11], v[52:53], v[14:15]
	s_waitcnt vmcnt(2)
	v_mov_b32_e32 v15, v56
	v_mov_b32_e32 v56, v55
	v_mov_b32_e32 v14, v54
	v_pk_mul_f32 v[22:23], v[16:17], v[56:57]
	s_nop 0
	v_pk_fma_f32 v[22:23], v[12:13], v[14:15], v[22:23] neg_lo:[0,0,1] neg_hi:[0,0,1]
	v_pk_mul_f32 v[14:15], v[16:17], v[14:15]
	s_nop 0
	v_pk_fma_f32 v[12:13], v[12:13], v[56:57], v[14:15]
	s_waitcnt vmcnt(1)
	v_mov_b32_e32 v14, v58
	v_mov_b32_e32 v15, v60
	v_mov_b32_e32 v60, v59
	v_pk_mul_f32 v[16:17], v[6:7], v[60:61]
	v_pk_mul_f32 v[6:7], v[6:7], v[14:15]
	v_pk_fma_f32 v[16:17], v[2:3], v[14:15], v[16:17] neg_lo:[0,0,1] neg_hi:[0,0,1]
	v_pk_fma_f32 v[6:7], v[2:3], v[60:61], v[6:7]
	s_waitcnt vmcnt(0)
	v_mov_b32_e32 v3, v64
	v_mov_b32_e32 v64, v63
	v_mov_b32_e32 v2, v62
	v_pk_mul_f32 v[14:15], v[8:9], v[64:65]
	s_nop 0
	v_pk_fma_f32 v[14:15], v[4:5], v[2:3], v[14:15] neg_lo:[0,0,1] neg_hi:[0,0,1]
	v_pk_mul_f32 v[2:3], v[8:9], v[2:3]
	s_nop 0
	v_pk_fma_f32 v[8:9], v[4:5], v[64:65], v[2:3]
	v_cvt_pk_bf16_f32 v2, v34, v35
	v_cvt_pk_bf16_f32 v3, v36, v37
	v_cvt_pk_bf16_f32 v4, v32, v33
	v_cvt_pk_bf16_f32 v5, v30, v31
	global_store_dwordx4 v[132:133], v[2:5], off offset:64
	s_nop 1
	v_cvt_pk_bf16_f32 v2, v24, v25
	v_cvt_pk_bf16_f32 v3, v22, v23
	v_cvt_pk_bf16_f32 v4, v16, v17
	v_cvt_pk_bf16_f32 v5, v14, v15
	global_store_dwordx4 v[132:133], v[2:5], off offset:80
	s_nop 1
	v_cvt_pk_bf16_f32 v2, v26, v27
	v_cvt_pk_bf16_f32 v3, v28, v29
	v_cvt_pk_bf16_f32 v4, v18, v19
	v_cvt_pk_bf16_f32 v5, v20, v21
	global_store_dwordx4 v[132:133], v[2:5], off offset:96
	s_nop 1
	v_cvt_pk_bf16_f32 v2, v10, v11
	v_cvt_pk_bf16_f32 v3, v12, v13
	v_cvt_pk_bf16_f32 v4, v6, v7
	v_cvt_pk_bf16_f32 v5, v8, v9
	global_store_dwordx4 v[132:133], v[2:5], off offset:112

; template <int N> DI void rmsnorm_inplace(float* v, const float* __restrict__ g) {
;   float s = 0.f;
; #pragma unroll
;   for (int i = 0; i < N; ++i) s += v[i] * v[i];
;   const float r = rsqrtf(s * (1.0f / N) + EPS);
; #pragma unroll
;   for (int i = 0; i < N; ++i) v[i] = v[i] * r * g[i];
; }
; DI void phase_mlaup(const Ctx& c) {
;     ...
;       } else if (isq) {
;         const int h0 = ((nt - 4) * 2 + half) * 2;
;         rmsnorm_inplace<32>(v, inl(c, 13, 96) + 64);
;         rmsnorm_inplace<32>(v + 32, inl(c, 13, 96) + 64);
;         rope32(v, rope + (size_t)pos * 16);
;         rope32(v + 32, rope + (size_t)pos * 16);
.LBB0_605:
	s_andn2_b64 vcc, exec, s[2:3]
	s_cbranch_vccnz .LBB0_607
	v_mov_b32_e32 v4, v69
	v_mov_b32_e32 v5, v53
	v_mov_b32_e32 v2, v68
	v_mov_b32_e32 v3, v52
	v_pk_mul_f32 v[4:5], v[4:5], v[4:5]
	v_readlane_b32 s2, v252, 7
	v_pk_fma_f32 v[2:3], v[2:3], v[2:3], v[4:5]
	v_mov_b32_e32 v4, v94
	v_mov_b32_e32 v5, v78
	v_pk_fma_f32 v[2:3], v[4:5], v[4:5], v[2:3]
	v_mov_b32_e32 v4, v95
	v_mov_b32_e32 v5, v79
	v_pk_fma_f32 v[2:3], v[4:5], v[4:5], v[2:3]
	v_mov_b32_e32 v4, v70
	v_mov_b32_e32 v5, v54
	v_pk_fma_f32 v[2:3], v[4:5], v[4:5], v[2:3]
	v_mov_b32_e32 v4, v71
	v_mov_b32_e32 v5, v55
	v_pk_fma_f32 v[2:3], v[4:5], v[4:5], v[2:3]
	v_mov_b32_e32 v4, v96
	v_mov_b32_e32 v5, v80
	v_pk_fma_f32 v[2:3], v[4:5], v[4:5], v[2:3]
	v_mov_b32_e32 v4, v97
	v_mov_b32_e32 v5, v81
	v_pk_fma_f32 v[2:3], v[4:5], v[4:5], v[2:3]
	v_mov_b32_e32 v4, v72
	v_mov_b32_e32 v5, v56
	v_pk_fma_f32 v[2:3], v[4:5], v[4:5], v[2:3]
	v_mov_b32_e32 v4, v73
	v_mov_b32_e32 v5, v57
	v_pk_fma_f32 v[2:3], v[4:5], v[4:5], v[2:3]
	v_mov_b32_e32 v4, v98
	v_mov_b32_e32 v5, v82
	v_pk_fma_f32 v[2:3], v[4:5], v[4:5], v[2:3]
	v_mov_b32_e32 v4, v99
	v_mov_b32_e32 v5, v83
	v_pk_fma_f32 v[2:3], v[4:5], v[4:5], v[2:3]
	v_mov_b32_e32 v4, v74
	v_mov_b32_e32 v5, v58
	v_pk_fma_f32 v[2:3], v[4:5], v[4:5], v[2:3]
	v_mov_b32_e32 v4, v75
	v_mov_b32_e32 v5, v59
	v_pk_fma_f32 v[26:27], v[4:5], v[4:5], v[2:3]
	v_mov_b32_e32 v28, v100
	v_lshlrev_b32_e32 v113, 7, v0
	global_load_dwordx4 v[18:21], v1, s[36:37] offset:272
	global_load_dwordx4 v[120:123], v1, s[36:37] offset:256
	global_load_dwordx4 v[22:25], v1, s[36:37] offset:336
	global_load_dwordx4 v[124:127], v1, s[36:37] offset:320
	v_readlane_b32 s3, v252, 8
	v_mov_b32_e32 v29, v84
	s_nop 3
	global_load_dwordx4 v[108:111], v113, s[2:3]
	global_load_dwordx4 v[2:5], v113, s[2:3] offset:16
	v_pk_fma_f32 v[26:27], v[28:29], v[28:29], v[26:27]
	v_mov_b32_e32 v28, v101
	v_mov_b32_e32 v29, v85
	v_pk_fma_f32 v[26:27], v[28:29], v[28:29], v[26:27]
	v_mov_b32_e32 v28, v76
	v_mov_b32_e32 v29, v60
	v_pk_fma_f32 v[26:27], v[28:29], v[28:29], v[26:27]
	v_mov_b32_e32 v28, v77
	v_mov_b32_e32 v29, v61
	v_pk_fma_f32 v[26:27], v[28:29], v[28:29], v[26:27]
	v_mov_b32_e32 v28, v44
	v_mov_b32_e32 v29, v86
	v_pk_fma_f32 v[26:27], v[28:29], v[28:29], v[26:27]
	v_mov_b32_e32 v28, v45
	v_mov_b32_e32 v29, v87
	v_pk_fma_f32 v[26:27], v[28:29], v[28:29], v[26:27]
	v_mov_b32_e32 v28, v38
	v_mov_b32_e32 v29, v62
	v_pk_mul_f32 v[6:7], v[88:89], v[88:89]
	v_pk_mul_f32 v[16:17], v[46:47], v[46:47]
	v_pk_fma_f32 v[34:35], v[28:29], v[28:29], v[26:27]
	v_mov_b32_e32 v36, v39
	v_mov_b32_e32 v37, v63
	global_load_dwordx4 v[26:29], v113, s[2:3] offset:48
	global_load_dwordx4 v[30:33], v113, s[2:3] offset:32
	v_pk_fma_f32 v[34:35], v[36:37], v[36:37], v[34:35]
	v_mov_b32_e32 v36, v16
	v_mov_b32_e32 v37, v6
	v_pk_mul_f32 v[8:9], v[64:65], v[64:65]
	v_pk_add_f32 v[34:35], v[36:37], v[34:35]
	v_pk_mul_f32 v[36:37], v[40:41], v[40:41]
	v_mov_b32_e32 v6, v17
	v_pk_add_f32 v[6:7], v[6:7], v[34:35]
	v_mov_b32_e32 v16, v36
	v_mov_b32_e32 v17, v8
	v_pk_mul_f32 v[10:11], v[90:91], v[90:91]
	v_pk_mul_f32 v[102:103], v[48:49], v[48:49]
	v_pk_add_f32 v[6:7], v[16:17], v[6:7]
	v_mov_b32_e32 v8, v37
	v_pk_add_f32 v[6:7], v[8:9], v[6:7]
	v_mov_b32_e32 v8, v102
	v_mov_b32_e32 v9, v10
	v_pk_mul_f32 v[12:13], v[66:67], v[66:67]
	v_pk_mul_f32 v[104:105], v[42:43], v[42:43]
	v_pk_add_f32 v[6:7], v[8:9], v[6:7]
	v_mov_b32_e32 v10, v103
	v_pk_add_f32 v[6:7], v[10:11], v[6:7]
	v_mov_b32_e32 v8, v104
	v_mov_b32_e32 v9, v12
	v_pk_mul_f32 v[14:15], v[92:93], v[92:93]
	v_pk_mul_f32 v[106:107], v[50:51], v[50:51]
	v_pk_add_f32 v[6:7], v[8:9], v[6:7]
	v_mov_b32_e32 v12, v105
	v_pk_add_f32 v[6:7], v[12:13], v[6:7]
	v_mov_b32_e32 v8, v106
	v_mov_b32_e32 v9, v14
	v_pk_add_f32 v[6:7], v[8:9], v[6:7]
	v_mov_b32_e32 v14, v107
	v_pk_add_f32 v[6:7], v[14:15], v[6:7]
	s_mov_b32 s0, 0x3d000000
	v_pk_fma_f32 v[10:11], v[6:7], s[0:1], v[198:199] op_sel_hi:[1,0,0]
	s_mov_b32 s0, 0x800000
	v_mul_f32_e32 v6, 0x4b800000, v11
	v_cmp_gt_f32_e32 vcc, s0, v11
	v_cmp_gt_f32_e64 s[0:1], s0, v10
	s_mov_b32 s27, 0xdd35000
	v_cndmask_b32_e32 v6, v11, v6, vcc
	v_rsq_f32_e32 v102, v6
	v_mul_f32_e32 v11, 0x4b800000, v10
	global_load_dwordx4 v[6:9], v1, s[36:37] offset:304
	global_load_dwordx4 v[14:17], v1, s[36:37] offset:288
	v_cndmask_b32_e64 v10, v10, v11, s[0:1]
	v_rsq_f32_e32 v104, v10
	global_load_dwordx4 v[10:13], v1, s[36:37] offset:352
	global_load_dwordx4 v[34:37], v113, s[2:3] offset:64
	v_mul_f32_e32 v103, 0x45800000, v102
	v_cndmask_b32_e32 v116, v102, v103, vcc
	v_mul_f32_e32 v102, 0x45800000, v104
	v_cndmask_b32_e64 v112, v104, v102, s[0:1]
	v_mul_f32_e32 v116, 0x3e16c740, v116
	v_mul_f32_e32 v112, 0x3e16c740, v112
	v_pk_mul_f32 v[104:105], v[60:61], v[116:117] op_sel_hi:[1,0]
	v_pk_mul_f32 v[102:103], v[52:53], v[116:117] op_sel_hi:[1,0]
	s_waitcnt vmcnt(8)
	v_pk_mul_f32 v[104:105], v[104:105], v[124:125]
	s_waitcnt vmcnt(7)
	v_mov_b32_e32 v119, v110
	v_mov_b32_e32 v110, v109
	v_pk_mul_f32 v[102:103], v[102:103], v[120:121]
	v_mov_b32_e32 v118, v108
	v_pk_mul_f32 v[106:107], v[104:105], v[110:111]
	v_pk_mul_f32 v[104:105], v[104:105], v[118:119]
	v_pk_fma_f32 v[108:109], v[102:103], v[118:119], v[106:107] neg_lo:[0,0,1] neg_hi:[0,0,1]
	v_pk_mul_f32 v[106:107], v[86:87], v[116:117] op_sel_hi:[1,0]
	v_pk_fma_f32 v[104:105], v[102:103], v[110:111], v[104:105]
	v_pk_mul_f32 v[102:103], v[78:79], v[116:117] op_sel_hi:[1,0]
	v_pk_mul_f32 v[106:107], v[106:107], v[126:127]
	s_waitcnt vmcnt(6)
; DI void rope32(float* v, const f32x2* __restrict__ tab  ) {
; #pragma unroll
;   for (int i = 0; i < 16; ++i) { const f32x2 cs = tab[i]; const float x1 = v[i], x2 = v[i + 16]; v[i] = x1 * cs.x - x2 * cs.y; v[i + 16] = x1 * cs.y + x2 * cs.x; }
; }
; DI void phase_mlaup(const Ctx& c) {
;     ...
;         const int h0 = ((nt - 4) * 2 + half) * 2;
;         rmsnorm_inplace<32>(v, inl(c, 13, 96) + 64);
;         rmsnorm_inplace<32>(v + 32, inl(c, 13, 96) + 64);
;         rope32(v, rope + (size_t)pos * 16);
;         rope32(v + 32, rope + (size_t)pos * 16);
	v_mov_b32_e32 v129, v4
	v_mov_b32_e32 v4, v3
	v_pk_mul_f32 v[102:103], v[102:103], v[122:123]
	v_mov_b32_e32 v128, v2
	v_pk_mul_f32 v[2:3], v[106:107], v[4:5]
	v_pk_mul_f32 v[132:133], v[76:77], v[112:113] op_sel_hi:[1,0]
	v_pk_fma_f32 v[114:115], v[102:103], v[128:129], v[2:3] neg_lo:[0,0,1] neg_hi:[0,0,1]
	v_pk_mul_f32 v[2:3], v[106:107], v[128:129]
	s_add_i32 s0, s26, s4
	v_pk_fma_f32 v[106:107], v[102:103], v[4:5], v[2:3]
	v_pk_mul_f32 v[102:103], v[62:63], v[116:117] op_sel_hi:[1,0]
	v_pk_mul_f32 v[2:3], v[54:55], v[116:117] op_sel_hi:[1,0]
	v_pk_mul_f32 v[130:131], v[102:103], v[22:23]
	v_pk_mul_f32 v[102:103], v[68:69], v[112:113] op_sel_hi:[1,0]
	v_pk_mul_f32 v[2:3], v[2:3], v[18:19]
	v_pk_mul_f32 v[134:135], v[102:103], v[120:121]
	v_pk_mul_f32 v[102:103], v[132:133], v[124:125]
	s_waitcnt vmcnt(4)
	v_mov_b32_e32 v133, v32
	v_mov_b32_e32 v32, v31
	v_mov_b32_e32 v132, v30
	v_pk_mul_f32 v[30:31], v[130:131], v[32:33]
	v_pk_mul_f32 v[124:125], v[102:103], v[110:111]
	v_pk_mul_f32 v[102:103], v[102:103], v[118:119]
	v_pk_fma_f32 v[120:121], v[2:3], v[132:133], v[30:31] neg_lo:[0,0,1] neg_hi:[0,0,1]
	v_pk_mul_f32 v[30:31], v[130:131], v[132:133]
	v_pk_fma_f32 v[102:103], v[134:135], v[110:111], v[102:103]
	v_pk_fma_f32 v[110:111], v[2:3], v[32:33], v[30:31]
	v_pk_fma_f32 v[30:31], v[134:135], v[118:119], v[124:125] neg_lo:[0,0,1] neg_hi:[0,0,1]
	v_pk_mul_f32 v[118:119], v[94:95], v[112:113] op_sel_hi:[1,0]
	v_pk_mul_f32 v[2:3], v[80:81], v[116:117] op_sel_hi:[1,0]
	v_pk_mul_f32 v[124:125], v[118:119], v[122:123]
	v_pk_mul_f32 v[118:119], v[88:89], v[116:117] op_sel_hi:[1,0]
	v_mov_b32_e32 v131, v28
	v_pk_mul_f32 v[118:119], v[118:119], v[24:25]
	v_mov_b32_e32 v28, v27
	v_pk_mul_f32 v[2:3], v[2:3], v[20:21]
	v_pk_mul_f32 v[122:123], v[44:45], v[112:113] op_sel_hi:[1,0]
	v_mov_b32_e32 v130, v26
	v_pk_mul_f32 v[26:27], v[118:119], v[28:29]
	v_pk_mul_f32 v[126:127], v[122:123], v[126:127]
	v_pk_fma_f32 v[122:123], v[2:3], v[130:131], v[26:27] neg_lo:[0,0,1] neg_hi:[0,0,1]
	v_pk_mul_f32 v[26:27], v[118:119], v[130:131]
	s_lshl_b32 s0, s0, 1
	v_pk_fma_f32 v[118:119], v[2:3], v[28:29], v[26:27]
	v_pk_mul_f32 v[2:3], v[126:127], v[4:5]
	s_lshl_b32 s1, s5, 3
	v_pk_fma_f32 v[26:27], v[124:125], v[128:129], v[2:3] neg_lo:[0,0,1] neg_hi:[0,0,1]
	v_pk_mul_f32 v[2:3], v[126:127], v[128:129]
	global_load_dwordx4 v[126:129], v113, s[2:3] offset:80
	v_pk_fma_f32 v[124:125], v[124:125], v[4:5], v[2:3]
	v_pk_mul_f32 v[2:3], v[70:71], v[112:113] op_sel_hi:[1,0]
	v_pk_mul_f32 v[4:5], v[38:39], v[112:113] op_sel_hi:[1,0]
	v_pk_mul_f32 v[134:135], v[2:3], v[18:19]
	v_pk_mul_f32 v[2:3], v[4:5], v[22:23]
	v_cvt_pk_bf16_f32 v104, v104, v105
	v_pk_mul_f32 v[22:23], v[2:3], v[32:33]
	v_pk_mul_f32 v[2:3], v[2:3], v[132:133]
	v_pk_fma_f32 v[22:23], v[134:135], v[132:133], v[22:23] neg_lo:[0,0,1] neg_hi:[0,0,1]
	v_pk_fma_f32 v[18:19], v[134:135], v[32:33], v[2:3]
	v_pk_mul_f32 v[32:33], v[56:57], v[116:117] op_sel_hi:[1,0]
	v_pk_mul_f32 v[132:133], v[46:47], v[112:113] op_sel_hi:[1,0]
	s_waitcnt vmcnt(3)
	v_pk_mul_f32 v[134:135], v[32:33], v[14:15]
	v_pk_mul_f32 v[32:33], v[96:97], v[112:113] op_sel_hi:[1,0]
	v_pk_mul_f32 v[132:133], v[132:133], v[24:25]
	v_pk_mul_f32 v[20:21], v[32:33], v[20:21]
	v_pk_mul_f32 v[24:25], v[132:133], v[28:29]
	global_load_dwordx4 v[2:5], v1, s[36:37] offset:368
	s_waitcnt vmcnt(2)
	v_mov_b32_e32 v136, v34
	v_mov_b32_e32 v137, v36
	v_mov_b32_e32 v36, v35
	v_pk_fma_f32 v[24:25], v[20:21], v[130:131], v[24:25] neg_lo:[0,0,1] neg_hi:[0,0,1]
	v_pk_mul_f32 v[34:35], v[132:133], v[130:131]
	global_load_dwordx4 v[130:133], v113, s[2:3] offset:96
	v_pk_mul_f32 v[32:33], v[64:65], v[116:117] op_sel_hi:[1,0]
	v_pk_fma_f32 v[20:21], v[20:21], v[28:29], v[34:35]
	v_pk_mul_f32 v[34:35], v[40:41], v[112:113] op_sel_hi:[1,0]
	v_pk_mul_f32 v[32:33], v[32:33], v[10:11]
	v_pk_mul_f32 v[28:29], v[72:73], v[112:113] op_sel_hi:[1,0]
	v_pk_mul_f32 v[10:11], v[34:35], v[10:11]
	v_pk_mul_f32 v[138:139], v[32:33], v[36:37]
	v_pk_mul_f32 v[32:33], v[32:33], v[136:137]
	v_pk_mul_f32 v[14:15], v[28:29], v[14:15]
	v_pk_mul_f32 v[28:29], v[10:11], v[36:37]
	v_pk_mul_f32 v[10:11], v[10:11], v[136:137]
	v_pk_fma_f32 v[32:33], v[134:135], v[36:37], v[32:33]
	v_pk_fma_f32 v[10:11], v[14:15], v[36:37], v[10:11]
	v_pk_fma_f32 v[34:35], v[134:135], v[136:137], v[138:139] neg_lo:[0,0,1] neg_hi:[0,0,1]
	v_pk_mul_f32 v[36:37], v[82:83], v[116:117] op_sel_hi:[1,0]
	v_pk_fma_f32 v[14:15], v[14:15], v[136:137], v[28:29] neg_lo:[0,0,1] neg_hi:[0,0,1]
	v_pk_mul_f32 v[28:29], v[90:91], v[116:117] op_sel_hi:[1,0]
	v_pk_mul_f32 v[134:135], v[98:99], v[112:113] op_sel_hi:[1,0]
	v_pk_mul_f32 v[36:37], v[36:37], v[16:17]
	v_pk_mul_f32 v[28:29], v[28:29], v[12:13]
	v_pk_mul_f32 v[16:17], v[134:135], v[16:17]
	v_cvt_pk_bf16_f32 v105, v106, v107
	v_cvt_pk_bf16_f32 v106, v110, v111
	v_cvt_pk_bf16_f32 v107, v118, v119
	v_cvt_pk_bf16_f32 v32, v32, v33
	s_waitcnt vmcnt(2)
; DI bf16_t* wsb(const Ctx& c, size_t off) { return (bf16_t*)(c.ws + off); }
; DI void phase_mlaup(const Ctx& c) {
;     ...
;         rope32(v, rope + (size_t)pos * 16);
;         rope32(v + 32, rope + (size_t)pos * 16);
;         store_bf16<32>(wsb(c, OFF_QA) + ((size_t)(seq * 8 + h0) * S + pos) * 96 + 64, v);
;         store_bf16<32>(wsb(c, OFF_QA) + ((size_t)(seq * 8 + h0 + 1) * S + pos) * 96 + 64, v + 32);
	v_mov_b32_e32 v134, v126
	v_mov_b32_e32 v135, v128
	v_mov_b32_e32 v128, v127
	v_pk_mul_f32 v[126:127], v[28:29], v[128:129]
	v_pk_mul_f32 v[28:29], v[28:29], v[134:135]
	v_pk_fma_f32 v[126:127], v[36:37], v[134:135], v[126:127] neg_lo:[0,0,1] neg_hi:[0,0,1]
	v_pk_fma_f32 v[28:29], v[36:37], v[128:129], v[28:29]
	v_pk_mul_f32 v[36:37], v[48:49], v[112:113] op_sel_hi:[1,0]
	v_cvt_pk_bf16_f32 v33, v28, v29
	v_pk_mul_f32 v[12:13], v[36:37], v[12:13]
	v_pk_mul_f32 v[36:37], v[58:59], v[116:117] op_sel_hi:[1,0]
	v_cvt_pk_bf16_f32 v28, v30, v31
	v_pk_mul_f32 v[136:137], v[36:37], v[6:7]
	v_pk_mul_f32 v[36:37], v[12:13], v[128:129]
	v_pk_mul_f32 v[12:13], v[12:13], v[134:135]
	v_cvt_pk_bf16_f32 v30, v22, v23
	v_pk_fma_f32 v[12:13], v[16:17], v[128:129], v[12:13]
	v_pk_mul_f32 v[128:129], v[66:67], v[116:117] op_sel_hi:[1,0]
	v_pk_fma_f32 v[16:17], v[16:17], v[134:135], v[36:37] neg_lo:[0,0,1] neg_hi:[0,0,1]
	s_waitcnt vmcnt(1)
	v_pk_mul_f32 v[128:129], v[128:129], v[2:3]
	v_cvt_pk_bf16_f32 v29, v26, v27
	v_cvt_pk_bf16_f32 v31, v24, v25
	s_waitcnt vmcnt(0)
	v_mov_b32_e32 v138, v130
	v_mov_b32_e32 v139, v132
	v_mov_b32_e32 v132, v131
	v_pk_mul_f32 v[130:131], v[128:129], v[132:133]
	v_pk_mul_f32 v[36:37], v[128:129], v[138:139]
	v_pk_mul_f32 v[128:129], v[74:75], v[112:113] op_sel_hi:[1,0]
	v_pk_fma_f32 v[36:37], v[136:137], v[132:133], v[36:37]
	v_pk_mul_f32 v[6:7], v[128:129], v[6:7]
	v_pk_mul_f32 v[128:129], v[42:43], v[112:113] op_sel_hi:[1,0]
	s_nop 0
	v_pk_mul_f32 v[2:3], v[128:129], v[2:3]
	v_pk_fma_f32 v[128:129], v[136:137], v[138:139], v[130:131] neg_lo:[0,0,1] neg_hi:[0,0,1]
	v_pk_mul_f32 v[134:135], v[2:3], v[132:133]
	v_pk_mul_f32 v[2:3], v[2:3], v[138:139]
	v_pk_mul_f32 v[130:131], v[84:85], v[116:117] op_sel_hi:[1,0]
	v_pk_fma_f32 v[2:3], v[6:7], v[132:133], v[2:3]
	v_pk_mul_f32 v[132:133], v[100:101], v[112:113] op_sel_hi:[1,0]
	v_pk_mul_f32 v[130:131], v[130:131], v[8:9]
	v_pk_fma_f32 v[6:7], v[6:7], v[138:139], v[134:135] neg_lo:[0,0,1] neg_hi:[0,0,1]
	v_pk_mul_f32 v[8:9], v[132:133], v[8:9]
	global_load_dwordx4 v[132:135], v113, s[2:3] offset:112
	s_add_i32 s2, s0, s1
	v_pk_mul_f32 v[116:117], v[92:93], v[116:117] op_sel_hi:[1,0]
	v_pk_mul_f32 v[112:113], v[50:51], v[112:113] op_sel_hi:[1,0]
	s_add_i32 s0, s2, -16
	v_pk_mul_f32 v[116:117], v[116:117], v[4:5]
	v_pk_mul_f32 v[4:5], v[112:113], v[4:5]
	s_ashr_i32 s1, s0, 31
	s_lshl_b64 s[0:1], s[0:1], s20
	s_movk_i32 s3, 0xc0
	v_cvt_pk_bf16_f32 v6, v6, v7
	s_waitcnt vmcnt(0)
	v_mov_b32_e32 v136, v132
	v_mov_b32_e32 v137, v134
	v_mov_b32_e32 v134, v133
	v_pk_mul_f32 v[132:133], v[116:117], v[134:135]
	v_pk_mul_f32 v[116:117], v[116:117], v[136:137]
	v_pk_mul_f32 v[112:113], v[4:5], v[134:135]
	v_pk_mul_f32 v[4:5], v[4:5], v[136:137]
	v_pk_fma_f32 v[132:133], v[130:131], v[136:137], v[132:133] neg_lo:[0,0,1] neg_hi:[0,0,1]
	v_pk_fma_f32 v[116:117], v[130:131], v[134:135], v[116:117]
	v_pk_fma_f32 v[130:131], v[8:9], v[136:137], v[112:113] neg_lo:[0,0,1] neg_hi:[0,0,1]
	v_pk_fma_f32 v[8:9], v[8:9], v[134:135], v[4:5]
	v_lshl_add_u64 v[4:5], s[0:1], 0, v[0:1]
	v_mov_b64_e32 v[134:135], s[94:95]
	v_mad_u64_u32 v[136:137], s[0:1], v4, s3, v[134:135]
	v_mad_i32_i24 v5, v5, s3, v137
	v_add_co_u32_e32 v4, vcc, s27, v136
	s_add_i32 s0, s2, -15
	v_cvt_pk_bf16_f32 v112, v108, v109
	v_cvt_pk_bf16_f32 v113, v114, v115
	v_cvt_pk_bf16_f32 v114, v120, v121
	v_cvt_pk_bf16_f32 v115, v122, v123
	v_addc_co_u32_e32 v5, vcc, 0, v5, vcc
	s_ashr_i32 s1, s0, 31
	global_store_dwordx4 v[4:5], v[112:115], off offset:2432
	s_lshl_b64 s[0:1], s[0:1], s20
	global_store_dwordx4 v[4:5], v[104:107], off offset:2464
	v_cvt_pk_bf16_f32 v112, v34, v35
	v_cvt_pk_bf16_f32 v113, v126, v127
	v_cvt_pk_bf16_f32 v114, v128, v129
	v_cvt_pk_bf16_f32 v115, v132, v133
	v_cvt_pk_bf16_f32 v34, v36, v37
	v_cvt_pk_bf16_f32 v35, v116, v117
	global_store_dwordx4 v[4:5], v[112:115], off offset:2448
	global_store_dwordx4 v[4:5], v[32:35], off offset:2480
	v_lshl_add_u64 v[4:5], s[0:1], 0, v[0:1]
	v_cvt_pk_bf16_f32 v7, v130, v131
	v_mad_u64_u32 v[32:33], s[0:1], v4, s3, v[134:135]
	v_mad_i32_i24 v4, v5, s3, v33
	v_add_co_u32_e32 v22, vcc, s27, v32
	v_cvt_pk_bf16_f32 v5, v16, v17
	s_nop 0
	v_addc_co_u32_e32 v23, vcc, 0, v4, vcc
	v_cvt_pk_bf16_f32 v4, v14, v15
	global_store_dwordx4 v[22:23], v[4:7], off offset:2448
	global_store_dwordx4 v[22:23], v[28:31], off offset:2432
	s_nop 0
	v_cvt_pk_bf16_f32 v4, v102, v103
	v_cvt_pk_bf16_f32 v5, v124, v125
	v_cvt_pk_bf16_f32 v6, v18, v19
	v_cvt_pk_bf16_f32 v7, v20, v21
	global_store_dwordx4 v[22:23], v[4:7], off offset:2464
	s_nop 1
	v_cvt_pk_bf16_f32 v4, v10, v11
	v_cvt_pk_bf16_f32 v5, v12, v13
	v_cvt_pk_bf16_f32 v6, v2, v3
	v_cvt_pk_bf16_f32 v7, v8, v9
	global_store_dwordx4 v[22:23], v[4:7], off offset:2480

; DI bf16_t* wsb(const Ctx& c, size_t off) { return (bf16_t*)(c.ws + off); }
; template <int N> DI void rmsnorm_inplace(float* v, const float* __restrict__ g) {
;   float s = 0.f;
; #pragma unroll
;   for (int i = 0; i < N; ++i) s += v[i] * v[i];
;   const float r = rsqrtf(s * (1.0f / N) + EPS);
; #pragma unroll
;   for (int i = 0; i < N; ++i) v[i] = v[i] * r * g[i];
; }
; DI void phase_mlaup(const Ctx& c) {
;     ...
;       if (isq && nt < 4) {
;         const int hh = nt * 2 + half;
;         rmsnorm_inplace<64>(v, inl(c, 13, 96));
;         store_bf16<64>(wsb(c, OFF_QA) + ((size_t)(seq * 8 + hh) * S + pos) * 96, v);
.LBB0_608:
	s_andn2_b64 vcc, exec, s[2:3]
	s_cbranch_vccnz .LBB0_592
	v_pk_mul_f32 v[2:3], v[52:53], v[52:53]
	v_pk_mul_f32 v[4:5], v[78:79], v[78:79]
	v_add_f32_e32 v2, v2, v3
	v_add_f32_e32 v2, v4, v2
	v_pk_mul_f32 v[6:7], v[54:55], v[54:55]
	v_add_f32_e32 v2, v5, v2
	v_add_f32_e32 v2, v6, v2
	v_pk_mul_f32 v[8:9], v[80:81], v[80:81]
	v_add_f32_e32 v2, v7, v2
	v_add_f32_e32 v2, v8, v2
	v_pk_mul_f32 v[10:11], v[56:57], v[56:57]
	v_add_f32_e32 v2, v9, v2
	v_add_f32_e32 v2, v10, v2
	v_pk_mul_f32 v[12:13], v[82:83], v[82:83]
	v_add_f32_e32 v10, v11, v2
	v_add_f32_e32 v10, v12, v10
	v_pk_mul_f32 v[14:15], v[58:59], v[58:59]
	v_add_f32_e32 v10, v13, v10
	v_add_f32_e32 v10, v14, v10
	v_pk_mul_f32 v[16:17], v[84:85], v[84:85]
	v_add_f32_e32 v10, v15, v10
	v_add_f32_e32 v10, v16, v10
	v_pk_mul_f32 v[18:19], v[60:61], v[60:61]
	v_add_f32_e32 v24, v17, v10
	v_add_f32_e32 v18, v18, v24
	v_pk_mul_f32 v[20:21], v[86:87], v[86:87]
	v_add_f32_e32 v18, v19, v18
	v_add_f32_e32 v18, v20, v18
	v_pk_mul_f32 v[22:23], v[62:63], v[62:63]
	v_add_f32_e32 v18, v21, v18
	v_add_f32_e32 v18, v22, v18
	v_pk_mul_f32 v[26:27], v[88:89], v[88:89]
	v_add_f32_e32 v32, v23, v18
	v_add_f32_e32 v26, v26, v32
	v_pk_mul_f32 v[28:29], v[64:65], v[64:65]
	global_load_dwordx4 v[2:5], v1, s[36:37] offset:16
	global_load_dwordx4 v[6:9], v1, s[36:37]
	v_add_f32_e32 v26, v27, v26
	v_add_f32_e32 v26, v28, v26
	v_pk_mul_f32 v[30:31], v[90:91], v[90:91]
	v_add_f32_e32 v26, v29, v26
	v_add_f32_e32 v26, v30, v26
	v_pk_mul_f32 v[34:35], v[66:67], v[66:67]
	global_load_dwordx4 v[10:13], v1, s[36:37] offset:48
	global_load_dwordx4 v[14:17], v1, s[36:37] offset:32
	v_add_f32_e32 v104, v31, v26
	v_add_f32_e32 v34, v34, v104
	v_pk_mul_f32 v[36:37], v[92:93], v[92:93]
	v_add_f32_e32 v34, v35, v34
	v_add_f32_e32 v34, v36, v34
	v_pk_mul_f32 v[102:103], v[68:69], v[68:69]
	global_load_dwordx4 v[18:21], v1, s[36:37] offset:80
	global_load_dwordx4 v[22:25], v1, s[36:37] offset:64
	v_add_f32_e32 v34, v37, v34
	v_add_f32_e32 v34, v102, v34
	v_pk_mul_f32 v[106:107], v[94:95], v[94:95]
	v_add_f32_e32 v112, v103, v34
	v_add_f32_e32 v106, v106, v112
	v_pk_mul_f32 v[108:109], v[70:71], v[70:71]
	global_load_dwordx4 v[26:29], v1, s[36:37] offset:112
	global_load_dwordx4 v[30:33], v1, s[36:37] offset:96
	v_add_f32_e32 v106, v107, v106
	v_add_f32_e32 v106, v108, v106
	v_pk_mul_f32 v[110:111], v[96:97], v[96:97]
	v_add_f32_e32 v106, v109, v106
	v_add_f32_e32 v106, v110, v106
	v_pk_mul_f32 v[114:115], v[72:73], v[72:73]
	global_load_dwordx4 v[34:37], v1, s[36:37] offset:144
	global_load_dwordx4 v[102:105], v1, s[36:37] offset:128
	v_add_f32_e32 v120, v111, v106
	v_add_f32_e32 v114, v114, v120
	v_pk_mul_f32 v[116:117], v[98:99], v[98:99]
	v_add_f32_e32 v114, v115, v114
	v_add_f32_e32 v114, v116, v114
	v_pk_mul_f32 v[118:119], v[74:75], v[74:75]
	global_load_dwordx4 v[106:109], v1, s[36:37] offset:176
	global_load_dwordx4 v[110:113], v1, s[36:37] offset:160
	v_add_f32_e32 v114, v117, v114
	v_add_f32_e32 v114, v118, v114
	v_pk_mul_f32 v[122:123], v[100:101], v[100:101]
	v_add_f32_e32 v140, v119, v114
	v_add_f32_e32 v122, v122, v140
	v_pk_mul_f32 v[124:125], v[76:77], v[76:77]
	global_load_dwordx4 v[114:117], v1, s[36:37] offset:208
	global_load_dwordx4 v[118:121], v1, s[36:37] offset:192
	v_add_f32_e32 v122, v123, v122
	v_add_f32_e32 v122, v124, v122
	v_pk_mul_f32 v[126:127], v[44:45], v[44:45]
	v_add_f32_e32 v122, v125, v122
	v_add_f32_e32 v122, v126, v122
	v_pk_mul_f32 v[128:129], v[38:39], v[38:39]
	v_add_f32_e32 v126, v127, v122
	global_load_dwordx4 v[122:125], v1, s[36:37] offset:224
	v_add_f32_e32 v126, v128, v126
	v_add_f32_e32 v140, v129, v126
	global_load_dwordx4 v[126:129], v1, s[36:37] offset:240
	v_pk_mul_f32 v[130:131], v[46:47], v[46:47]
	v_pk_mul_f32 v[132:133], v[40:41], v[40:41]
	v_add_f32_e32 v130, v130, v140
	v_add_f32_e32 v130, v131, v130
	v_add_f32_e32 v130, v132, v130
	v_pk_mul_f32 v[134:135], v[48:49], v[48:49]
	v_add_f32_e32 v130, v133, v130
	v_add_f32_e32 v130, v134, v130
	v_pk_mul_f32 v[136:137], v[42:43], v[42:43]
	v_add_f32_e32 v130, v135, v130
	v_add_f32_e32 v130, v136, v130
	v_pk_mul_f32 v[138:139], v[50:51], v[50:51]
	v_add_f32_e32 v130, v137, v130
	v_add_f32_e32 v130, v138, v130
	v_add_f32_e32 v130, v139, v130
	v_fmamk_f32 v130, v130, 0x3c800000, v198
	s_mov_b32 s0, 0x800000
	v_mul_f32_e32 v131, 0x4b800000, v130
	v_cmp_gt_f32_e32 vcc, s0, v130
	s_lshl_b32 s0, s5, 3
	s_or_b32 s0, s0, s26
	v_cndmask_b32_e32 v130, v130, v131, vcc
	v_rsq_f32_e32 v130, v130
	s_add_i32 s0, s0, s4
	s_ashr_i32 s1, s0, 31
	s_lshl_b64 s[0:1], s[0:1], s20
	v_mul_f32_e32 v131, 0x45800000, v130
	v_cndmask_b32_e32 v130, v130, v131, vcc
	v_mul_f32_e32 v130, 0x3e16c740, v130
	v_pk_mul_f32 v[52:53], v[52:53], v[130:131] op_sel_hi:[1,0]
	s_movk_i32 s2, 0xc0
	s_waitcnt vmcnt(14)
	v_pk_mul_f32 v[6:7], v[52:53], v[6:7]
	v_pk_mul_f32 v[52:53], v[78:79], v[130:131] op_sel_hi:[1,0]
	s_nop 0
	v_pk_mul_f32 v[8:9], v[52:53], v[8:9]
	v_pk_mul_f32 v[52:53], v[54:55], v[130:131] op_sel_hi:[1,0]
	s_nop 0
	v_pk_mul_f32 v[52:53], v[52:53], v[2:3]
	v_pk_mul_f32 v[2:3], v[80:81], v[130:131] op_sel_hi:[1,0]
	s_nop 0
	v_pk_mul_f32 v[54:55], v[2:3], v[4:5]
	v_pk_mul_f32 v[2:3], v[56:57], v[130:131] op_sel_hi:[1,0]
	s_waitcnt vmcnt(12)
; DI bf16_t* wsb(const Ctx& c, size_t off) { return (bf16_t*)(c.ws + off); }
; DI void phase_mlaup(const Ctx& c) {
;     ...
;       if (isq && nt < 4) {
;         const int hh = nt * 2 + half;
;         rmsnorm_inplace<64>(v, inl(c, 13, 96));
;         store_bf16<64>(wsb(c, OFF_QA) + ((size_t)(seq * 8 + hh) * S + pos) * 96, v);
	v_pk_mul_f32 v[14:15], v[2:3], v[14:15]
	v_pk_mul_f32 v[2:3], v[82:83], v[130:131] op_sel_hi:[1,0]
	s_nop 0
	v_pk_mul_f32 v[16:17], v[2:3], v[16:17]
	v_pk_mul_f32 v[2:3], v[58:59], v[130:131] op_sel_hi:[1,0]
	s_nop 0
	v_pk_mul_f32 v[10:11], v[2:3], v[10:11]
	v_pk_mul_f32 v[2:3], v[84:85], v[130:131] op_sel_hi:[1,0]
	s_nop 0
	v_pk_mul_f32 v[12:13], v[2:3], v[12:13]
	v_pk_mul_f32 v[2:3], v[60:61], v[130:131] op_sel_hi:[1,0]
	s_waitcnt vmcnt(10)
	v_pk_mul_f32 v[22:23], v[2:3], v[22:23]
	v_pk_mul_f32 v[2:3], v[86:87], v[130:131] op_sel_hi:[1,0]
	s_nop 0
	v_pk_mul_f32 v[24:25], v[2:3], v[24:25]
	v_pk_mul_f32 v[2:3], v[62:63], v[130:131] op_sel_hi:[1,0]
	s_nop 0
	v_pk_mul_f32 v[18:19], v[2:3], v[18:19]
	v_pk_mul_f32 v[2:3], v[88:89], v[130:131] op_sel_hi:[1,0]
	s_nop 0
	v_pk_mul_f32 v[20:21], v[2:3], v[20:21]
	v_pk_mul_f32 v[2:3], v[64:65], v[130:131] op_sel_hi:[1,0]
	s_waitcnt vmcnt(8)
	v_pk_mul_f32 v[30:31], v[2:3], v[30:31]
	v_pk_mul_f32 v[2:3], v[90:91], v[130:131] op_sel_hi:[1,0]
	s_nop 0
	v_pk_mul_f32 v[32:33], v[2:3], v[32:33]
	v_pk_mul_f32 v[2:3], v[66:67], v[130:131] op_sel_hi:[1,0]
	s_nop 0
	v_pk_mul_f32 v[26:27], v[2:3], v[26:27]
	v_pk_mul_f32 v[2:3], v[92:93], v[130:131] op_sel_hi:[1,0]
	s_nop 0
	v_pk_mul_f32 v[28:29], v[2:3], v[28:29]
	v_pk_mul_f32 v[2:3], v[68:69], v[130:131] op_sel_hi:[1,0]
	s_waitcnt vmcnt(6)
	v_pk_mul_f32 v[56:57], v[2:3], v[102:103]
	v_pk_mul_f32 v[2:3], v[94:95], v[130:131] op_sel_hi:[1,0]
	s_nop 0
	v_pk_mul_f32 v[58:59], v[2:3], v[104:105]
	v_pk_mul_f32 v[2:3], v[70:71], v[130:131] op_sel_hi:[1,0]
	s_nop 0
	v_pk_mul_f32 v[34:35], v[2:3], v[34:35]
	v_pk_mul_f32 v[2:3], v[96:97], v[130:131] op_sel_hi:[1,0]
	s_nop 0
	v_pk_mul_f32 v[36:37], v[2:3], v[36:37]
	v_pk_mul_f32 v[2:3], v[72:73], v[130:131] op_sel_hi:[1,0]
	s_waitcnt vmcnt(4)
	v_pk_mul_f32 v[60:61], v[2:3], v[110:111]
	v_pk_mul_f32 v[2:3], v[98:99], v[130:131] op_sel_hi:[1,0]
	s_nop 0
	v_pk_mul_f32 v[62:63], v[2:3], v[112:113]
	v_pk_mul_f32 v[2:3], v[74:75], v[130:131] op_sel_hi:[1,0]
	s_nop 0
	v_pk_mul_f32 v[64:65], v[2:3], v[106:107]
	v_pk_mul_f32 v[2:3], v[100:101], v[130:131] op_sel_hi:[1,0]
	s_nop 0
	v_pk_mul_f32 v[66:67], v[2:3], v[108:109]
	v_pk_mul_f32 v[2:3], v[76:77], v[130:131] op_sel_hi:[1,0]
	s_waitcnt vmcnt(2)
	v_pk_mul_f32 v[68:69], v[2:3], v[118:119]
	v_pk_mul_f32 v[2:3], v[44:45], v[130:131] op_sel_hi:[1,0]
	s_nop 0
	v_pk_mul_f32 v[44:45], v[2:3], v[120:121]
	v_pk_mul_f32 v[2:3], v[38:39], v[130:131] op_sel_hi:[1,0]
	s_nop 0
	v_pk_mul_f32 v[38:39], v[2:3], v[114:115]
	v_pk_mul_f32 v[2:3], v[46:47], v[130:131] op_sel_hi:[1,0]
	s_nop 0
	v_pk_mul_f32 v[46:47], v[2:3], v[116:117]
	v_pk_mul_f32 v[2:3], v[40:41], v[130:131] op_sel_hi:[1,0]
	s_waitcnt vmcnt(1)
	v_pk_mul_f32 v[40:41], v[2:3], v[122:123]
	v_pk_mul_f32 v[2:3], v[48:49], v[130:131] op_sel_hi:[1,0]
	s_nop 0
	v_pk_mul_f32 v[48:49], v[2:3], v[124:125]
	v_pk_mul_f32 v[2:3], v[42:43], v[130:131] op_sel_hi:[1,0]
	s_waitcnt vmcnt(0)
	v_pk_mul_f32 v[42:43], v[2:3], v[126:127]
	v_pk_mul_f32 v[2:3], v[50:51], v[130:131] op_sel_hi:[1,0]
	s_nop 0
	v_pk_mul_f32 v[50:51], v[2:3], v[128:129]
	v_lshl_add_u64 v[2:3], s[0:1], 0, v[0:1]
	v_readlane_b32 s0, v250, 40
	v_readlane_b32 s1, v250, 41
	s_nop 1
	v_mov_b64_e32 v[4:5], s[0:1]
	v_mad_u64_u32 v[70:71], s[0:1], v2, s2, v[4:5]
	v_mad_i32_i24 v71, v3, s2, v71
	v_cvt_pk_bf16_f32 v2, v6, v7
	v_cvt_pk_bf16_f32 v3, v8, v9
	v_cvt_pk_bf16_f32 v4, v52, v53
	v_cvt_pk_bf16_f32 v5, v54, v55
	global_store_dwordx4 v[70:71], v[2:5], off
	s_nop 1
	v_cvt_pk_bf16_f32 v2, v14, v15
	v_cvt_pk_bf16_f32 v3, v16, v17
	v_cvt_pk_bf16_f32 v4, v10, v11
	v_cvt_pk_bf16_f32 v5, v12, v13
	global_store_dwordx4 v[70:71], v[2:5], off offset:16
	s_nop 1
	v_cvt_pk_bf16_f32 v2, v22, v23
	v_cvt_pk_bf16_f32 v3, v24, v25
	v_cvt_pk_bf16_f32 v4, v18, v19
	v_cvt_pk_bf16_f32 v5, v20, v21
	global_store_dwordx4 v[70:71], v[2:5], off offset:32
	s_nop 1
	v_cvt_pk_bf16_f32 v2, v30, v31
	v_cvt_pk_bf16_f32 v3, v32, v33
	v_cvt_pk_bf16_f32 v4, v26, v27
	v_cvt_pk_bf16_f32 v5, v28, v29
	global_store_dwordx4 v[70:71], v[2:5], off offset:48
	s_nop 1
	v_cvt_pk_bf16_f32 v2, v56, v57
	v_cvt_pk_bf16_f32 v3, v58, v59
	v_cvt_pk_bf16_f32 v4, v34, v35
	v_cvt_pk_bf16_f32 v5, v36, v37
	global_store_dwordx4 v[70:71], v[2:5], off offset:64
	s_nop 1
	v_cvt_pk_bf16_f32 v2, v60, v61
	v_cvt_pk_bf16_f32 v3, v62, v63
	v_cvt_pk_bf16_f32 v4, v64, v65
	v_cvt_pk_bf16_f32 v5, v66, v67
	global_store_dwordx4 v[70:71], v[2:5], off offset:80
	s_nop 1
	v_cvt_pk_bf16_f32 v2, v68, v69
	v_cvt_pk_bf16_f32 v3, v44, v45
	v_cvt_pk_bf16_f32 v4, v38, v39
	v_cvt_pk_bf16_f32 v5, v46, v47
	global_store_dwordx4 v[70:71], v[2:5], off offset:96
	s_nop 1
	v_cvt_pk_bf16_f32 v2, v40, v41
	v_cvt_pk_bf16_f32 v3, v48, v49
	v_cvt_pk_bf16_f32 v4, v42, v43
	v_cvt_pk_bf16_f32 v5, v50, v51
	global_store_dwordx4 v[70:71], v[2:5], off offset:112
	s_branch .LBB0_592

; template <int DQK, bool BAND, int QT> ...
;     ...
;         float mx = s[0][qt][0];
; #pragma unroll
;         for (int r = 1; r < 16; ++r) mx = fmaxf(mx, s[0][qt][r]);
; #pragma unroll
;         for (int r = 0; r < 16; ++r) mx = fmaxf(mx, s[1][qt][r]);
;         mx = fmaxf(mx, __shfl_xor(mx, 32));
;         if (__builtin_amdgcn_ballot_w64(mx > m[qt] + th) != 0) {
;           const float mn = fmaxf(m[qt], mx);
;           const float alpha = __builtin_amdgcn_exp2f((m[qt] - mn) * cc);
;           m[qt] = mn;
;           l[qt] *= alpha;
; #pragma unroll
;           for (int r = 0; r < 16; ++r) { o[0][qt][r] *= alpha; o[1][qt][r] *= alpha; }
;         }
.Lgqa_dma_noload:
	s_nop 7
	s_setprio 0
	v_max_f32_e32 v203, v82, v83
	v_max_f32_e32 v253, v114, v115
	v_max3_f32 v203, v203, v84, v85
	v_max3_f32 v253, v253, v116, v117
	v_max3_f32 v203, v203, v86, v87
	v_max3_f32 v253, v253, v118, v119
	v_max3_f32 v203, v203, v88, v89
	v_max3_f32 v253, v253, v120, v121
	v_max3_f32 v203, v203, v90, v91
	v_max3_f32 v253, v253, v122, v123
	v_max3_f32 v203, v203, v92, v93
	v_max3_f32 v253, v253, v124, v125
	v_max3_f32 v203, v203, v94, v95
	v_max3_f32 v253, v253, v126, v127
	v_max3_f32 v203, v203, v96, v97
	v_max3_f32 v253, v253, v128, v129
	v_max3_f32 v203, v203, v66, v67
	v_max3_f32 v253, v253, v98, v99
	v_max3_f32 v203, v203, v68, v69
	v_max3_f32 v253, v253, v100, v101
	v_max3_f32 v203, v203, v70, v71
	v_max3_f32 v253, v253, v102, v103
	v_max3_f32 v203, v203, v72, v73
	v_max3_f32 v253, v253, v104, v105
	v_max3_f32 v203, v203, v74, v75
	v_max3_f32 v253, v253, v106, v107
	v_max3_f32 v203, v203, v76, v77
	v_max3_f32 v253, v253, v108, v109
	v_max3_f32 v203, v203, v78, v79
	v_max3_f32 v253, v253, v110, v111
	v_max3_f32 v203, v203, v80, v81
	v_max3_f32 v253, v253, v112, v113
	v_cmp_gt_f32_e32 vcc, v203, v136
	s_cbranch_vccz .Lgqa_nr0
	ds_bpermute_b32 v254, v179, v203
	s_waitcnt lgkmcnt(0)
	v_max_f32_e32 v254, v254, v254
	v_max_f32_e32 v203, v203, v254
	v_max_f32_e32 v254, v197, v197
	v_max_f32_e32 v203, v254, v203
	v_sub_f32_e32 v197, v197, v203
	v_mul_f32_e32 v197, 1.0, v197
	v_exp_f32_e32 v254, v197
	v_mov_b32_e32 v197, v203
	v_add_f32_e32 v136, 0x41000000, v203
	v_mul_f32_e32 v138, -1.0, v203
	v_pk_mul_f32 v[64:65], v[64:65], v[254:255] op_sel_hi:[1,0]
	v_pk_mul_f32 v[62:63], v[62:63], v[254:255] op_sel_hi:[1,0]
	v_pk_mul_f32 v[60:61], v[60:61], v[254:255] op_sel_hi:[1,0]
	v_pk_mul_f32 v[58:59], v[58:59], v[254:255] op_sel_hi:[1,0]
	v_pk_mul_f32 v[56:57], v[56:57], v[254:255] op_sel_hi:[1,0]
	v_pk_mul_f32 v[54:55], v[54:55], v[254:255] op_sel_hi:[1,0]
	v_pk_mul_f32 v[52:53], v[52:53], v[254:255] op_sel_hi:[1,0]
	v_pk_mul_f32 v[50:51], v[50:51], v[254:255] op_sel_hi:[1,0]
	v_pk_mul_f32 v[48:49], v[48:49], v[254:255] op_sel_hi:[1,0]
	v_pk_mul_f32 v[46:47], v[46:47], v[254:255] op_sel_hi:[1,0]
	v_pk_mul_f32 v[44:45], v[44:45], v[254:255] op_sel_hi:[1,0]
	v_pk_mul_f32 v[42:43], v[42:43], v[254:255] op_sel_hi:[1,0]
	v_pk_mul_f32 v[40:41], v[40:41], v[254:255] op_sel_hi:[1,0]
	v_pk_mul_f32 v[38:39], v[38:39], v[254:255] op_sel_hi:[1,0]
	v_pk_mul_f32 v[36:37], v[36:37], v[254:255] op_sel_hi:[1,0]
	v_pk_mul_f32 v[34:35], v[34:35], v[254:255] op_sel_hi:[1,0]
	v_mbcnt_lo_u32_b32 v255, -1, 0
	v_mbcnt_hi_u32_b32 v255, -1, v255
	v_add_u32_e32 v255, 16, v255
	v_lshlrev_b32_e32 v255, 2, v255
	ds_bpermute_b32 v255, v255, v254
	s_waitcnt lgkmcnt(0)
	v_mul_f32_e32 v240, v240, v254
	v_mul_f32_e32 v241, v241, v255
.Lgqa_nr0:
	v_cmp_gt_f32_e32 vcc, v253, v137
	s_cbranch_vccz .Lgqa_nr1
	ds_bpermute_b32 v254, v179, v253
	s_waitcnt lgkmcnt(0)
	v_max_f32_e32 v254, v254, v254
	v_max_f32_e32 v253, v253, v254
	v_max_f32_e32 v254, v202, v202
	v_max_f32_e32 v253, v254, v253
	v_sub_f32_e32 v202, v202, v253
	v_mul_f32_e32 v202, 1.0, v202
	v_exp_f32_e32 v254, v202
	v_mov_b32_e32 v202, v253
	v_add_f32_e32 v137, 0x41000000, v253
	v_mul_f32_e32 v139, -1.0, v253
	v_pk_mul_f32 v[32:33], v[32:33], v[254:255] op_sel_hi:[1,0]
	v_pk_mul_f32 v[30:31], v[30:31], v[254:255] op_sel_hi:[1,0]
	v_pk_mul_f32 v[28:29], v[28:29], v[254:255] op_sel_hi:[1,0]
	v_pk_mul_f32 v[26:27], v[26:27], v[254:255] op_sel_hi:[1,0]
	v_pk_mul_f32 v[24:25], v[24:25], v[254:255] op_sel_hi:[1,0]
	v_pk_mul_f32 v[22:23], v[22:23], v[254:255] op_sel_hi:[1,0]
	v_pk_mul_f32 v[20:21], v[20:21], v[254:255] op_sel_hi:[1,0]
	v_pk_mul_f32 v[18:19], v[18:19], v[254:255] op_sel_hi:[1,0]
	v_pk_mul_f32 v[16:17], v[16:17], v[254:255] op_sel_hi:[1,0]
	v_pk_mul_f32 v[14:15], v[14:15], v[254:255] op_sel_hi:[1,0]
	v_pk_mul_f32 v[12:13], v[12:13], v[254:255] op_sel_hi:[1,0]
	v_pk_mul_f32 v[10:11], v[10:11], v[254:255] op_sel_hi:[1,0]
	v_pk_mul_f32 v[8:9], v[8:9], v[254:255] op_sel_hi:[1,0]
	v_pk_mul_f32 v[6:7], v[6:7], v[254:255] op_sel_hi:[1,0]
	v_pk_mul_f32 v[4:5], v[4:5], v[254:255] op_sel_hi:[1,0]
	v_pk_mul_f32 v[2:3], v[2:3], v[254:255] op_sel_hi:[1,0]
	v_mbcnt_lo_u32_b32 v255, -1, 0
	v_mbcnt_hi_u32_b32 v255, -1, v255
	v_add_u32_e32 v255, 16, v255
	v_lshlrev_b32_e32 v255, 2, v255
	ds_bpermute_b32 v255, v255, v254
	s_waitcnt lgkmcnt(0)
	v_mul_f32_e32 v236, v236, v254
	v_mul_f32_e32 v237, v237, v255
; #define MFMA(a, b, c) __builtin_amdgcn_mfma_f32_32x32x16_bf16((a), (b), (c), 0, 0, 0)
; DI unsigned pk2(float a, float b) { f32x2 v = {a, b}; bf16x2_t r = __builtin_convertvector(v, bf16x2_t); return __builtin_bit_cast(unsigned, r); }
; template <int DQK, bool BAND, int QT> ...
;     ...
;         const float mc = -m[qt] * cc;
;         float ls = 0.f;
; #pragma unroll
;         for (int a = 0; a < 2; ++a) {
; #pragma unroll
;           for (int r = 0; r < 16; ++r) { const float pv = __builtin_amdgcn_exp2f(fmaf(s[a][qt][r], cc, mc)); s[a][qt][r] = pv; ls += pv; }
; #pragma unroll
;           for (int s2 = 0; s2 < 2; ++s2) {
;             u32x4 pk;
;             pk.x = pk2(s[a][qt][8 * s2 + 0], s[a][qt][8 * s2 + 1]);
;             pk.y = pk2(s[a][qt][8 * s2 + 2], s[a][qt][8 * s2 + 3]);
;             pk.z = pk2(s[a][qt][8 * s2 + 4], s[a][qt][8 * s2 + 5]);
;             pk.w = pk2(s[a][qt][8 * s2 + 6], s[a][qt][8 * s2 + 7]);
;             pf[qt][a * 2 + s2] = __builtin_bit_cast(bf16x8, pk);
;           }
;         }
;         l[qt] += ls;
;       }
;       __builtin_amdgcn_s_setprio(0);
;       if (more) lstore(lds + ((it + 1) & 1) * ST);
; #pragma unroll
;       for (int ks = 0; ks < 4; ++ks) {
;         const bf16x8 v0 = *(const bf16x8*)(st + v_rd + ks * 32);
;         const bf16x8 v1 = *(const bf16x8*)(st + v_rd + 32 * LROW + ks * 32);
; #pragma unroll
;         for (int qt = 0; qt < QT; ++qt) {
;           o[0][qt] = MFMA(v0, pf[qt][ks], o[0][qt]);
;           o[1][qt] = MFMA(v1, pf[qt][ks], o[1][qt]);
;         }
;       }
.Lgqa_nr1:
	v_sub_f32_e32 v82, v82, v197
	v_sub_f32_e32 v114, v114, v202
	v_sub_f32_e32 v83, v83, v197
	v_sub_f32_e32 v115, v115, v202
	v_sub_f32_e32 v84, v84, v197
	v_sub_f32_e32 v116, v116, v202
	v_sub_f32_e32 v85, v85, v197
	v_sub_f32_e32 v117, v117, v202
	v_sub_f32_e32 v86, v86, v197
	v_sub_f32_e32 v118, v118, v202
	v_sub_f32_e32 v87, v87, v197
	v_sub_f32_e32 v119, v119, v202
	v_sub_f32_e32 v88, v88, v197
	v_sub_f32_e32 v120, v120, v202
	v_sub_f32_e32 v89, v89, v197
	v_sub_f32_e32 v121, v121, v202
	v_exp_f32_e32 v82, v82
	v_exp_f32_e32 v114, v114
	v_exp_f32_e32 v83, v83
	v_exp_f32_e32 v115, v115
	v_exp_f32_e32 v84, v84
	v_exp_f32_e32 v116, v116
	v_exp_f32_e32 v85, v85
	v_exp_f32_e32 v117, v117
	v_exp_f32_e32 v86, v86
	v_exp_f32_e32 v118, v118
	v_exp_f32_e32 v87, v87
	v_exp_f32_e32 v119, v119
	v_exp_f32_e32 v88, v88
	v_exp_f32_e32 v120, v120
	v_exp_f32_e32 v89, v89
	v_exp_f32_e32 v121, v121
	v_sub_f32_e32 v90, v90, v197
	v_sub_f32_e32 v122, v122, v202
	v_sub_f32_e32 v91, v91, v197
	v_sub_f32_e32 v123, v123, v202
	v_sub_f32_e32 v92, v92, v197
	v_sub_f32_e32 v124, v124, v202
	v_sub_f32_e32 v93, v93, v197
	v_sub_f32_e32 v125, v125, v202
	v_sub_f32_e32 v94, v94, v197
	v_sub_f32_e32 v126, v126, v202
	v_sub_f32_e32 v95, v95, v197
	v_sub_f32_e32 v127, v127, v202
	v_sub_f32_e32 v96, v96, v197
	v_sub_f32_e32 v128, v128, v202
	v_sub_f32_e32 v97, v97, v197
	v_sub_f32_e32 v129, v129, v202
	v_exp_f32_e32 v90, v90
	v_exp_f32_e32 v122, v122
	v_exp_f32_e32 v91, v91
	v_exp_f32_e32 v123, v123
	v_exp_f32_e32 v92, v92
	v_exp_f32_e32 v124, v124
	v_exp_f32_e32 v93, v93
	v_exp_f32_e32 v125, v125
	v_exp_f32_e32 v94, v94
	v_exp_f32_e32 v126, v126
	v_exp_f32_e32 v95, v95
	v_exp_f32_e32 v127, v127
	v_exp_f32_e32 v96, v96
	v_exp_f32_e32 v128, v128
	v_exp_f32_e32 v97, v97
	v_exp_f32_e32 v129, v129
	v_cvt_pk_bf16_f32 v82, v82, v83
	v_cvt_pk_bf16_f32 v114, v114, v115
	v_cvt_pk_bf16_f32 v83, v84, v85
	v_cvt_pk_bf16_f32 v115, v116, v117
	v_cvt_pk_bf16_f32 v84, v86, v87
	v_cvt_pk_bf16_f32 v116, v118, v119
	v_cvt_pk_bf16_f32 v85, v88, v89
	v_cvt_pk_bf16_f32 v117, v120, v121
	v_sub_f32_e32 v66, v66, v197
	v_sub_f32_e32 v98, v98, v202
	v_sub_f32_e32 v67, v67, v197
	v_sub_f32_e32 v99, v99, v202
	v_sub_f32_e32 v68, v68, v197
	v_sub_f32_e32 v100, v100, v202
	v_sub_f32_e32 v69, v69, v197
	v_sub_f32_e32 v101, v101, v202
	v_sub_f32_e32 v70, v70, v197
	v_sub_f32_e32 v102, v102, v202
	v_sub_f32_e32 v71, v71, v197
	v_sub_f32_e32 v103, v103, v202
	v_sub_f32_e32 v72, v72, v197
	v_sub_f32_e32 v104, v104, v202
	v_sub_f32_e32 v73, v73, v197
	v_sub_f32_e32 v105, v105, v202
	v_exp_f32_e32 v66, v66
	v_exp_f32_e32 v98, v98
	v_exp_f32_e32 v67, v67
	v_exp_f32_e32 v99, v99
	v_exp_f32_e32 v68, v68
	v_exp_f32_e32 v100, v100
	v_exp_f32_e32 v69, v69
	v_exp_f32_e32 v101, v101
	v_exp_f32_e32 v70, v70
	v_exp_f32_e32 v102, v102
	v_exp_f32_e32 v71, v71
	v_exp_f32_e32 v103, v103
	v_exp_f32_e32 v72, v72
	v_exp_f32_e32 v104, v104
	v_exp_f32_e32 v73, v73
	v_exp_f32_e32 v105, v105
	v_cvt_pk_bf16_f32 v90, v90, v91
	v_cvt_pk_bf16_f32 v122, v122, v123
	v_cvt_pk_bf16_f32 v91, v92, v93
	v_cvt_pk_bf16_f32 v123, v124, v125
	v_cvt_pk_bf16_f32 v92, v94, v95
	v_cvt_pk_bf16_f32 v124, v126, v127
	v_cvt_pk_bf16_f32 v93, v96, v97
	v_cvt_pk_bf16_f32 v125, v128, v129
	v_sub_f32_e32 v74, v74, v197
	v_sub_f32_e32 v106, v106, v202
	v_sub_f32_e32 v75, v75, v197
	v_sub_f32_e32 v107, v107, v202
	v_sub_f32_e32 v76, v76, v197
	v_sub_f32_e32 v108, v108, v202
	v_sub_f32_e32 v77, v77, v197
	v_sub_f32_e32 v109, v109, v202
	v_sub_f32_e32 v78, v78, v197
	v_sub_f32_e32 v110, v110, v202
	v_sub_f32_e32 v79, v79, v197
	v_sub_f32_e32 v111, v111, v202
	v_sub_f32_e32 v80, v80, v197
	v_sub_f32_e32 v112, v112, v202
	v_sub_f32_e32 v81, v81, v197
	v_sub_f32_e32 v113, v113, v202
	v_exp_f32_e32 v74, v74
	v_exp_f32_e32 v106, v106
	v_exp_f32_e32 v75, v75
	v_exp_f32_e32 v107, v107
	v_exp_f32_e32 v76, v76
	v_exp_f32_e32 v108, v108
	v_exp_f32_e32 v77, v77
	v_exp_f32_e32 v109, v109
	v_exp_f32_e32 v78, v78
	v_exp_f32_e32 v110, v110
	v_exp_f32_e32 v79, v79
	v_exp_f32_e32 v111, v111
	v_exp_f32_e32 v80, v80
	v_exp_f32_e32 v112, v112
	v_exp_f32_e32 v81, v81
	v_exp_f32_e32 v113, v113
	v_cvt_pk_bf16_f32 v66, v66, v67
	v_cvt_pk_bf16_f32 v98, v98, v99
	v_cvt_pk_bf16_f32 v67, v68, v69
	v_cvt_pk_bf16_f32 v99, v100, v101
	v_cvt_pk_bf16_f32 v68, v70, v71
	v_cvt_pk_bf16_f32 v100, v102, v103
	v_cvt_pk_bf16_f32 v69, v72, v73
	v_cvt_pk_bf16_f32 v101, v104, v105
	v_cvt_pk_bf16_f32 v74, v74, v75
	v_cvt_pk_bf16_f32 v106, v106, v107
	v_cvt_pk_bf16_f32 v75, v76, v77
	v_cvt_pk_bf16_f32 v107, v108, v109
	v_cvt_pk_bf16_f32 v76, v78, v79
	v_cvt_pk_bf16_f32 v108, v110, v111
	v_cvt_pk_bf16_f32 v77, v80, v81
	v_cvt_pk_bf16_f32 v109, v112, v113
	s_setprio 2
	ds_read_b128 v[86:89], v183 offset:9216
	ds_read_b128 v[94:97], v183 offset:13824
	ds_read_b128 v[70:73], v183 offset:9248
	ds_read_b128 v[78:81], v183 offset:13856
	ds_read_b128 v[118:121], v183 offset:9280
	ds_read_b128 v[126:129], v183 offset:13888
	ds_read_b128 v[102:105], v183 offset:9312
	ds_read_b128 v[110:113], v183 offset:13920
	s_waitcnt lgkmcnt(7)
	v_mfma_f32_32x32x16_bf16 v[50:65], v[86:89], v[82:85], v[50:65]
	v_mfma_f32_32x32x16_bf16 v[18:33], v[86:89], v[114:117], v[18:33]
	s_waitcnt lgkmcnt(6)
	v_mfma_f32_32x32x16_bf16 v[34:49], v[94:97], v[82:85], v[34:49]
	v_mfma_f32_32x32x16_bf16 v[2:17], v[94:97], v[114:117], v[2:17]
	v_mfma_f32_16x16x32_bf16 v[240:243], v[244:247], v[82:85], v[240:243]
	v_mfma_f32_16x16x32_bf16 v[236:239], v[244:247], v[114:117], v[236:239]
	s_waitcnt lgkmcnt(5)
	v_mfma_f32_32x32x16_bf16 v[50:65], v[70:73], v[90:93], v[50:65]
	v_mfma_f32_32x32x16_bf16 v[18:33], v[70:73], v[122:125], v[18:33]
	s_waitcnt lgkmcnt(4)
	v_mfma_f32_32x32x16_bf16 v[34:49], v[78:81], v[90:93], v[34:49]
	v_mfma_f32_32x32x16_bf16 v[2:17], v[78:81], v[122:125], v[2:17]
	v_mfma_f32_16x16x32_bf16 v[240:243], v[244:247], v[90:93], v[240:243]
	v_mfma_f32_16x16x32_bf16 v[236:239], v[244:247], v[122:125], v[236:239]
	s_waitcnt lgkmcnt(3)
	v_mfma_f32_32x32x16_bf16 v[50:65], v[118:121], v[66:69], v[50:65]
	v_mfma_f32_32x32x16_bf16 v[18:33], v[118:121], v[98:101], v[18:33]
	s_waitcnt lgkmcnt(2)
	v_mfma_f32_32x32x16_bf16 v[34:49], v[126:129], v[66:69], v[34:49]
	v_mfma_f32_32x32x16_bf16 v[2:17], v[126:129], v[98:101], v[2:17]
	v_mfma_f32_16x16x32_bf16 v[240:243], v[244:247], v[66:69], v[240:243]
	v_mfma_f32_16x16x32_bf16 v[236:239], v[244:247], v[98:101], v[236:239]
	s_bitcmp1_b32 s1, 0
	s_cselect_b32 s7, -1, 1
	s_mulk_i32 s7, 0x4800
	v_add_u32_e32 v185, s7, v185
	v_add_u32_e32 v183, s7, v183
	s_add_i32 s1, s1, 1
	s_add_i32 s6, s6, 64
	s_waitcnt vmcnt(0) lgkmcnt(0)
	s_barrier
; #define MFMA(a, b, c) __builtin_amdgcn_mfma_f32_32x32x16_bf16((a), (b), (c), 0, 0, 0)
; template <int DQK, bool BAND, int QT> ...
;     ...
;       for (int ks = 0; ks < 4; ++ks) {
;         const bf16x8 v0 = *(const bf16x8*)(st + v_rd + ks * 32);
;         const bf16x8 v1 = *(const bf16x8*)(st + v_rd + 32 * LROW + ks * 32);
; #pragma unroll
;         for (int qt = 0; qt < QT; ++qt) {
;           o[0][qt] = MFMA(v0, pf[qt][ks], o[0][qt]);
;           o[1][qt] = MFMA(v1, pf[qt][ks], o[1][qt]);
;         }
;       }
;     } else {
;       if (more) lstore(lds + ((it + 1) & 1) * ST);
;     }
;     __syncthreads();
;   }
; #pragma unroll
;   for (int qt = 0; qt < QT; ++qt) {
;     const float lt = l[qt] + __shfl_xor(l[qt], 32);
	v_mfma_f32_32x32x16_bf16 v[50:65], v[102:105], v[74:77], v[50:65]
	v_mfma_f32_32x32x16_bf16 v[18:33], v[102:105], v[106:109], v[18:33]
	v_mfma_f32_32x32x16_bf16 v[34:49], v[110:113], v[74:77], v[34:49]
	v_mfma_f32_32x32x16_bf16 v[2:17], v[110:113], v[106:109], v[2:17]
	v_mfma_f32_16x16x32_bf16 v[240:243], v[244:247], v[74:77], v[240:243]
	v_mfma_f32_16x16x32_bf16 v[236:239], v[244:247], v[106:109], v[236:239]
	s_cmp_lg_u32 s21, s1
	s_cbranch_scc1 .Lgqa_top
	s_setprio 0
	s_nop 7
	v_mbcnt_lo_u32_b32 v254, -1, 0
	v_mbcnt_hi_u32_b32 v254, -1, v254
	v_and_b32_e32 v255, 15, v254
	v_lshlrev_b32_e32 v255, 2, v255
	ds_bpermute_b32 v203, v255, v240
	ds_bpermute_b32 v253, v255, v241
	s_waitcnt lgkmcnt(0)
	v_cmp_gt_u32_e32 vcc, 16, v254
	s_nop 1
	v_cndmask_b32_e32 v187, v253, v203, vcc
	v_cmp_gt_u32_e32 vcc, 32, v254
	s_nop 1
	v_cndmask_b32_e32 v187, 0, v187, vcc
	ds_bpermute_b32 v203, v255, v236
	ds_bpermute_b32 v253, v255, v237
	s_waitcnt lgkmcnt(0)
	v_cmp_gt_u32_e32 vcc, 16, v254
	s_nop 1
	v_cndmask_b32_e32 v181, v253, v203, vcc
	v_cmp_gt_u32_e32 vcc, 32, v254
	s_nop 1
	v_cndmask_b32_e32 v181, 0, v181, vcc

; template <int DQK, bool BAND, int QT> ...
;     ...
;         float mx = s[0][qt][0];
; #pragma unroll
;         for (int r = 1; r < 16; ++r) mx = fmaxf(mx, s[0][qt][r]);
; #pragma unroll
;         for (int r = 0; r < 16; ++r) mx = fmaxf(mx, s[1][qt][r]);
;         mx = fmaxf(mx, __shfl_xor(mx, 32));
;         if (__builtin_amdgcn_ballot_w64(mx > m[qt] + th) != 0) {
;           const float mn = fmaxf(m[qt], mx);
;           const float alpha = __builtin_amdgcn_exp2f((m[qt] - mn) * cc);
;           m[qt] = mn;
;           l[qt] *= alpha;
; #pragma unroll
;           for (int r = 0; r < 16; ++r) { o[0][qt][r] *= alpha; o[1][qt][r] *= alpha; }
;         }
.Lmla_dma_noload:
	s_nop 7
	s_setprio 0
	v_max_f32_e32 v239, v82, v83
	v_max_f32_e32 v253, v114, v115
	v_max3_f32 v239, v239, v84, v85
	v_max3_f32 v253, v253, v116, v117
	v_max3_f32 v239, v239, v86, v87
	v_max3_f32 v253, v253, v118, v119
	v_max3_f32 v239, v239, v88, v89
	v_max3_f32 v253, v253, v120, v121
	v_max3_f32 v239, v239, v90, v91
	v_max3_f32 v253, v253, v122, v123
	v_max3_f32 v239, v239, v92, v93
	v_max3_f32 v253, v253, v124, v125
	v_max3_f32 v239, v239, v94, v95
	v_max3_f32 v253, v253, v126, v127
	v_max3_f32 v239, v239, v96, v97
	v_max3_f32 v253, v253, v128, v129
	v_max3_f32 v239, v239, v66, v67
	v_max3_f32 v253, v253, v98, v99
	v_max3_f32 v239, v239, v68, v69
	v_max3_f32 v253, v253, v100, v101
	v_max3_f32 v239, v239, v70, v71
	v_max3_f32 v253, v253, v102, v103
	v_max3_f32 v239, v239, v72, v73
	v_max3_f32 v253, v253, v104, v105
	v_max3_f32 v239, v239, v74, v75
	v_max3_f32 v253, v253, v106, v107
	v_max3_f32 v239, v239, v76, v77
	v_max3_f32 v253, v253, v108, v109
	v_max3_f32 v239, v239, v78, v79
	v_max3_f32 v253, v253, v110, v111
	v_max3_f32 v239, v239, v80, v81
	v_max3_f32 v253, v253, v112, v113
	v_cmp_gt_f32_e32 vcc, v239, v208
	s_cbranch_vccz .Lmla_nr0
	ds_bpermute_b32 v254, v203, v239
	s_waitcnt lgkmcnt(0)
	v_max_f32_e32 v254, v254, v254
	v_max_f32_e32 v239, v239, v254
	v_max_f32_e32 v254, v237, v237
	v_max_f32_e32 v239, v254, v239
	v_sub_f32_e32 v237, v237, v239
	v_mul_f32_e32 v237, 1.0, v237
	v_exp_f32_e32 v254, v237
	v_mov_b32_e32 v237, v239
	v_add_f32_e32 v208, 0x41000000, v239
	v_mul_f32_e32 v210, -1.0, v239
	v_pk_mul_f32 v[64:65], v[64:65], v[254:255] op_sel_hi:[1,0]
	v_pk_mul_f32 v[62:63], v[62:63], v[254:255] op_sel_hi:[1,0]
	v_pk_mul_f32 v[60:61], v[60:61], v[254:255] op_sel_hi:[1,0]
	v_pk_mul_f32 v[58:59], v[58:59], v[254:255] op_sel_hi:[1,0]
	v_pk_mul_f32 v[56:57], v[56:57], v[254:255] op_sel_hi:[1,0]
	v_pk_mul_f32 v[54:55], v[54:55], v[254:255] op_sel_hi:[1,0]
	v_pk_mul_f32 v[52:53], v[52:53], v[254:255] op_sel_hi:[1,0]
	v_pk_mul_f32 v[50:51], v[50:51], v[254:255] op_sel_hi:[1,0]
	v_pk_mul_f32 v[48:49], v[48:49], v[254:255] op_sel_hi:[1,0]
	v_pk_mul_f32 v[46:47], v[46:47], v[254:255] op_sel_hi:[1,0]
	v_pk_mul_f32 v[44:45], v[44:45], v[254:255] op_sel_hi:[1,0]
	v_pk_mul_f32 v[42:43], v[42:43], v[254:255] op_sel_hi:[1,0]
	v_pk_mul_f32 v[40:41], v[40:41], v[254:255] op_sel_hi:[1,0]
	v_pk_mul_f32 v[38:39], v[38:39], v[254:255] op_sel_hi:[1,0]
	v_pk_mul_f32 v[36:37], v[36:37], v[254:255] op_sel_hi:[1,0]
	v_pk_mul_f32 v[34:35], v[34:35], v[254:255] op_sel_hi:[1,0]
	v_mbcnt_lo_u32_b32 v255, -1, 0
	v_mbcnt_hi_u32_b32 v255, -1, v255
	v_add_u32_e32 v255, 16, v255
	v_lshlrev_b32_e32 v255, 2, v255
	ds_bpermute_b32 v255, v255, v254
	s_waitcnt lgkmcnt(0)
	v_mul_f32_e32 v134, v134, v254
	v_mul_f32_e32 v135, v135, v255
.Lmla_nr0:
	v_cmp_gt_f32_e32 vcc, v253, v209
	s_cbranch_vccz .Lmla_nr1
	ds_bpermute_b32 v254, v203, v253
	s_waitcnt lgkmcnt(0)
	v_max_f32_e32 v254, v254, v254
	v_max_f32_e32 v253, v253, v254
	v_max_f32_e32 v254, v238, v238
	v_max_f32_e32 v253, v254, v253
	v_sub_f32_e32 v238, v238, v253
	v_mul_f32_e32 v238, 1.0, v238
	v_exp_f32_e32 v254, v238
	v_mov_b32_e32 v238, v253
	v_add_f32_e32 v209, 0x41000000, v253
	v_mul_f32_e32 v211, -1.0, v253
	v_pk_mul_f32 v[32:33], v[32:33], v[254:255] op_sel_hi:[1,0]
	v_pk_mul_f32 v[30:31], v[30:31], v[254:255] op_sel_hi:[1,0]
	v_pk_mul_f32 v[28:29], v[28:29], v[254:255] op_sel_hi:[1,0]
	v_pk_mul_f32 v[26:27], v[26:27], v[254:255] op_sel_hi:[1,0]
	v_pk_mul_f32 v[24:25], v[24:25], v[254:255] op_sel_hi:[1,0]
	v_pk_mul_f32 v[22:23], v[22:23], v[254:255] op_sel_hi:[1,0]
	v_pk_mul_f32 v[20:21], v[20:21], v[254:255] op_sel_hi:[1,0]
	v_pk_mul_f32 v[18:19], v[18:19], v[254:255] op_sel_hi:[1,0]
	v_pk_mul_f32 v[16:17], v[16:17], v[254:255] op_sel_hi:[1,0]
	v_pk_mul_f32 v[14:15], v[14:15], v[254:255] op_sel_hi:[1,0]
	v_pk_mul_f32 v[12:13], v[12:13], v[254:255] op_sel_hi:[1,0]
	v_pk_mul_f32 v[10:11], v[10:11], v[254:255] op_sel_hi:[1,0]
	v_pk_mul_f32 v[8:9], v[8:9], v[254:255] op_sel_hi:[1,0]
	v_pk_mul_f32 v[6:7], v[6:7], v[254:255] op_sel_hi:[1,0]
	v_pk_mul_f32 v[4:5], v[4:5], v[254:255] op_sel_hi:[1,0]
	v_pk_mul_f32 v[2:3], v[2:3], v[254:255] op_sel_hi:[1,0]
	v_mbcnt_lo_u32_b32 v255, -1, 0
	v_mbcnt_hi_u32_b32 v255, -1, v255
	v_add_u32_e32 v255, 16, v255
	v_lshlrev_b32_e32 v255, 2, v255
	ds_bpermute_b32 v255, v255, v254
	s_waitcnt lgkmcnt(0)
	v_mul_f32_e32 v138, v138, v254
	v_mul_f32_e32 v139, v139, v255
; #define MFMA(a, b, c) __builtin_amdgcn_mfma_f32_32x32x16_bf16((a), (b), (c), 0, 0, 0)
; DI unsigned pk2(float a, float b) { f32x2 v = {a, b}; bf16x2_t r = __builtin_convertvector(v, bf16x2_t); return __builtin_bit_cast(unsigned, r); }
; template <int DQK, bool BAND, int QT> ...
;     ...
;         const float mc = -m[qt] * cc;
;         float ls = 0.f;
; #pragma unroll
;         for (int a = 0; a < 2; ++a) {
; #pragma unroll
;           for (int r = 0; r < 16; ++r) { const float pv = __builtin_amdgcn_exp2f(fmaf(s[a][qt][r], cc, mc)); s[a][qt][r] = pv; ls += pv; }
; #pragma unroll
;           for (int s2 = 0; s2 < 2; ++s2) {
;             u32x4 pk;
;             pk.x = pk2(s[a][qt][8 * s2 + 0], s[a][qt][8 * s2 + 1]);
;             pk.y = pk2(s[a][qt][8 * s2 + 2], s[a][qt][8 * s2 + 3]);
;             pk.z = pk2(s[a][qt][8 * s2 + 4], s[a][qt][8 * s2 + 5]);
;             pk.w = pk2(s[a][qt][8 * s2 + 6], s[a][qt][8 * s2 + 7]);
;             pf[qt][a * 2 + s2] = __builtin_bit_cast(bf16x8, pk);
;           }
;         }
;         l[qt] += ls;
;       }
;       __builtin_amdgcn_s_setprio(0);
;       if (more) lstore(lds + ((it + 1) & 1) * ST);
; #pragma unroll
;       for (int ks = 0; ks < 4; ++ks) {
;         const bf16x8 v0 = *(const bf16x8*)(st + v_rd + ks * 32);
;         const bf16x8 v1 = *(const bf16x8*)(st + v_rd + 32 * LROW + ks * 32);
; #pragma unroll
;         for (int qt = 0; qt < QT; ++qt) {
;           o[0][qt] = MFMA(v0, pf[qt][ks], o[0][qt]);
;           o[1][qt] = MFMA(v1, pf[qt][ks], o[1][qt]);
;         }
;       }
.Lmla_nr1:
	v_sub_f32_e32 v82, v82, v237
	v_sub_f32_e32 v114, v114, v238
	v_sub_f32_e32 v83, v83, v237
	v_sub_f32_e32 v115, v115, v238
	v_sub_f32_e32 v84, v84, v237
	v_sub_f32_e32 v116, v116, v238
	v_sub_f32_e32 v85, v85, v237
	v_sub_f32_e32 v117, v117, v238
	v_sub_f32_e32 v86, v86, v237
	v_sub_f32_e32 v118, v118, v238
	v_sub_f32_e32 v87, v87, v237
	v_sub_f32_e32 v119, v119, v238
	v_sub_f32_e32 v88, v88, v237
	v_sub_f32_e32 v120, v120, v238
	v_sub_f32_e32 v89, v89, v237
	v_sub_f32_e32 v121, v121, v238
	v_exp_f32_e32 v82, v82
	v_exp_f32_e32 v114, v114
	v_exp_f32_e32 v83, v83
	v_exp_f32_e32 v115, v115
	v_exp_f32_e32 v84, v84
	v_exp_f32_e32 v116, v116
	v_exp_f32_e32 v85, v85
	v_exp_f32_e32 v117, v117
	v_exp_f32_e32 v86, v86
	v_exp_f32_e32 v118, v118
	v_exp_f32_e32 v87, v87
	v_exp_f32_e32 v119, v119
	v_exp_f32_e32 v88, v88
	v_exp_f32_e32 v120, v120
	v_exp_f32_e32 v89, v89
	v_exp_f32_e32 v121, v121
	v_sub_f32_e32 v90, v90, v237
	v_sub_f32_e32 v122, v122, v238
	v_sub_f32_e32 v91, v91, v237
	v_sub_f32_e32 v123, v123, v238
	v_sub_f32_e32 v92, v92, v237
	v_sub_f32_e32 v124, v124, v238
	v_sub_f32_e32 v93, v93, v237
	v_sub_f32_e32 v125, v125, v238
	v_sub_f32_e32 v94, v94, v237
	v_sub_f32_e32 v126, v126, v238
	v_sub_f32_e32 v95, v95, v237
	v_sub_f32_e32 v127, v127, v238
	v_sub_f32_e32 v96, v96, v237
	v_sub_f32_e32 v128, v128, v238
	v_sub_f32_e32 v97, v97, v237
	v_sub_f32_e32 v129, v129, v238
	v_exp_f32_e32 v90, v90
	v_exp_f32_e32 v122, v122
	v_exp_f32_e32 v91, v91
	v_exp_f32_e32 v123, v123
	v_exp_f32_e32 v92, v92
	v_exp_f32_e32 v124, v124
	v_exp_f32_e32 v93, v93
	v_exp_f32_e32 v125, v125
	v_exp_f32_e32 v94, v94
	v_exp_f32_e32 v126, v126
	v_exp_f32_e32 v95, v95
	v_exp_f32_e32 v127, v127
	v_exp_f32_e32 v96, v96
	v_exp_f32_e32 v128, v128
	v_exp_f32_e32 v97, v97
	v_exp_f32_e32 v129, v129
	v_cvt_pk_bf16_f32 v82, v82, v83
	v_cvt_pk_bf16_f32 v114, v114, v115
	v_cvt_pk_bf16_f32 v83, v84, v85
	v_cvt_pk_bf16_f32 v115, v116, v117
	v_cvt_pk_bf16_f32 v84, v86, v87
	v_cvt_pk_bf16_f32 v116, v118, v119
	v_cvt_pk_bf16_f32 v85, v88, v89
	v_cvt_pk_bf16_f32 v117, v120, v121
	v_sub_f32_e32 v66, v66, v237
	v_sub_f32_e32 v98, v98, v238
	v_sub_f32_e32 v67, v67, v237
	v_sub_f32_e32 v99, v99, v238
	v_sub_f32_e32 v68, v68, v237
	v_sub_f32_e32 v100, v100, v238
	v_sub_f32_e32 v69, v69, v237
	v_sub_f32_e32 v101, v101, v238
	v_sub_f32_e32 v70, v70, v237
	v_sub_f32_e32 v102, v102, v238
	v_sub_f32_e32 v71, v71, v237
	v_sub_f32_e32 v103, v103, v238
	v_sub_f32_e32 v72, v72, v237
	v_sub_f32_e32 v104, v104, v238
	v_sub_f32_e32 v73, v73, v237
	v_sub_f32_e32 v105, v105, v238
	v_exp_f32_e32 v66, v66
	v_exp_f32_e32 v98, v98
	v_exp_f32_e32 v67, v67
	v_exp_f32_e32 v99, v99
	v_exp_f32_e32 v68, v68
	v_exp_f32_e32 v100, v100
	v_exp_f32_e32 v69, v69
	v_exp_f32_e32 v101, v101
	v_exp_f32_e32 v70, v70
	v_exp_f32_e32 v102, v102
	v_exp_f32_e32 v71, v71
	v_exp_f32_e32 v103, v103
	v_exp_f32_e32 v72, v72
	v_exp_f32_e32 v104, v104
	v_exp_f32_e32 v73, v73
	v_exp_f32_e32 v105, v105
	v_cvt_pk_bf16_f32 v90, v90, v91
	v_cvt_pk_bf16_f32 v122, v122, v123
	v_cvt_pk_bf16_f32 v91, v92, v93
	v_cvt_pk_bf16_f32 v123, v124, v125
	v_cvt_pk_bf16_f32 v92, v94, v95
	v_cvt_pk_bf16_f32 v124, v126, v127
	v_cvt_pk_bf16_f32 v93, v96, v97
	v_cvt_pk_bf16_f32 v125, v128, v129
	v_sub_f32_e32 v74, v74, v237
	v_sub_f32_e32 v106, v106, v238
	v_sub_f32_e32 v75, v75, v237
	v_sub_f32_e32 v107, v107, v238
	v_sub_f32_e32 v76, v76, v237
	v_sub_f32_e32 v108, v108, v238
	v_sub_f32_e32 v77, v77, v237
	v_sub_f32_e32 v109, v109, v238
	v_sub_f32_e32 v78, v78, v237
	v_sub_f32_e32 v110, v110, v238
	v_sub_f32_e32 v79, v79, v237
	v_sub_f32_e32 v111, v111, v238
	v_sub_f32_e32 v80, v80, v237
	v_sub_f32_e32 v112, v112, v238
	v_sub_f32_e32 v81, v81, v237
	v_sub_f32_e32 v113, v113, v238
	v_exp_f32_e32 v74, v74
	v_exp_f32_e32 v106, v106
	v_exp_f32_e32 v75, v75
	v_exp_f32_e32 v107, v107
	v_exp_f32_e32 v76, v76
	v_exp_f32_e32 v108, v108
	v_exp_f32_e32 v77, v77
	v_exp_f32_e32 v109, v109
	v_exp_f32_e32 v78, v78
	v_exp_f32_e32 v110, v110
	v_exp_f32_e32 v79, v79
	v_exp_f32_e32 v111, v111
	v_exp_f32_e32 v80, v80
	v_exp_f32_e32 v112, v112
	v_exp_f32_e32 v81, v81
	v_exp_f32_e32 v113, v113
	v_cvt_pk_bf16_f32 v66, v66, v67
	v_cvt_pk_bf16_f32 v98, v98, v99
	v_cvt_pk_bf16_f32 v67, v68, v69
	v_cvt_pk_bf16_f32 v99, v100, v101
	v_cvt_pk_bf16_f32 v68, v70, v71
	v_cvt_pk_bf16_f32 v100, v102, v103
	v_cvt_pk_bf16_f32 v69, v72, v73
	v_cvt_pk_bf16_f32 v101, v104, v105
	v_cvt_pk_bf16_f32 v74, v74, v75
	v_cvt_pk_bf16_f32 v106, v106, v107
	v_cvt_pk_bf16_f32 v75, v76, v77
	v_cvt_pk_bf16_f32 v107, v108, v109
	v_cvt_pk_bf16_f32 v76, v78, v79
	v_cvt_pk_bf16_f32 v108, v110, v111
	v_cvt_pk_bf16_f32 v77, v80, v81
	v_cvt_pk_bf16_f32 v109, v112, v113
	s_setprio 2
	ds_read_b128 v[86:89], v234 offset:13312
	ds_read_b128 v[94:97], v234 offset:17920
	ds_read_b128 v[70:73], v234 offset:13344
	ds_read_b128 v[78:81], v234 offset:17952
	ds_read_b128 v[118:121], v234 offset:13376
	ds_read_b128 v[126:129], v234 offset:17984
	ds_read_b128 v[102:105], v234 offset:13408
	ds_read_b128 v[110:113], v234 offset:18016
	s_waitcnt lgkmcnt(7)
	v_mfma_f32_32x32x16_bf16 v[50:65], v[86:89], v[82:85], v[50:65]
	v_mfma_f32_32x32x16_bf16 v[18:33], v[86:89], v[114:117], v[18:33]
	s_waitcnt lgkmcnt(6)
	v_mfma_f32_32x32x16_bf16 v[34:49], v[94:97], v[82:85], v[34:49]
	v_mfma_f32_32x32x16_bf16 v[2:17], v[94:97], v[114:117], v[2:17]
	v_mfma_f32_16x16x32_bf16 v[134:137], v[130:133], v[82:85], v[134:137]
	v_mfma_f32_16x16x32_bf16 v[138:141], v[130:133], v[114:117], v[138:141]
	s_waitcnt lgkmcnt(5)
	v_mfma_f32_32x32x16_bf16 v[50:65], v[70:73], v[90:93], v[50:65]
	v_mfma_f32_32x32x16_bf16 v[18:33], v[70:73], v[122:125], v[18:33]
	s_waitcnt lgkmcnt(4)
	v_mfma_f32_32x32x16_bf16 v[34:49], v[78:81], v[90:93], v[34:49]
	v_mfma_f32_32x32x16_bf16 v[2:17], v[78:81], v[122:125], v[2:17]
	v_mfma_f32_16x16x32_bf16 v[134:137], v[130:133], v[90:93], v[134:137]
	v_mfma_f32_16x16x32_bf16 v[138:141], v[130:133], v[122:125], v[138:141]
	s_waitcnt lgkmcnt(3)
	v_mfma_f32_32x32x16_bf16 v[50:65], v[118:121], v[66:69], v[50:65]
	v_mfma_f32_32x32x16_bf16 v[18:33], v[118:121], v[98:101], v[18:33]
	s_waitcnt lgkmcnt(2)
	v_mfma_f32_32x32x16_bf16 v[34:49], v[126:129], v[66:69], v[34:49]
	v_mfma_f32_32x32x16_bf16 v[2:17], v[126:129], v[98:101], v[2:17]
	v_mfma_f32_16x16x32_bf16 v[134:137], v[130:133], v[66:69], v[134:137]
	v_mfma_f32_16x16x32_bf16 v[138:141], v[130:133], v[98:101], v[138:141]
	s_bitcmp1_b32 s1, 0
	s_cselect_b32 s7, -1, 1
	s_mulk_i32 s7, 0x5800
	v_add_u32_e32 v235, s7, v235
	v_add_u32_e32 v234, s7, v234
	s_add_i32 s1, s1, 1
	s_add_i32 s6, s6, 64
	s_waitcnt vmcnt(0) lgkmcnt(0)
	s_barrier
; #define MFMA(a, b, c) __builtin_amdgcn_mfma_f32_32x32x16_bf16((a), (b), (c), 0, 0, 0)
; template <int DQK, bool BAND, int QT> ...
;     ...
;       for (int ks = 0; ks < 4; ++ks) {
;         const bf16x8 v0 = *(const bf16x8*)(st + v_rd + ks * 32);
;         const bf16x8 v1 = *(const bf16x8*)(st + v_rd + 32 * LROW + ks * 32);
; #pragma unroll
;         for (int qt = 0; qt < QT; ++qt) {
;           o[0][qt] = MFMA(v0, pf[qt][ks], o[0][qt]);
;           o[1][qt] = MFMA(v1, pf[qt][ks], o[1][qt]);
;         }
;       }
;     } else {
;       if (more) lstore(lds + ((it + 1) & 1) * ST);
;     }
;     __syncthreads();
;   }
; #pragma unroll
;   for (int qt = 0; qt < QT; ++qt) {
;     const float lt = l[qt] + __shfl_xor(l[qt], 32);
	v_mfma_f32_32x32x16_bf16 v[50:65], v[102:105], v[74:77], v[50:65]
	v_mfma_f32_32x32x16_bf16 v[18:33], v[102:105], v[106:109], v[18:33]
	v_mfma_f32_32x32x16_bf16 v[34:49], v[110:113], v[74:77], v[34:49]
	v_mfma_f32_32x32x16_bf16 v[2:17], v[110:113], v[106:109], v[2:17]
	v_mfma_f32_16x16x32_bf16 v[134:137], v[130:133], v[74:77], v[134:137]
	v_mfma_f32_16x16x32_bf16 v[138:141], v[130:133], v[106:109], v[138:141]
	s_cmp_lg_u32 s21, s1
	s_cbranch_scc1 .Lmla_top
	s_setprio 0
	s_nop 7
	v_mbcnt_lo_u32_b32 v254, -1, 0
	v_mbcnt_hi_u32_b32 v254, -1, v254
	v_and_b32_e32 v255, 15, v254
	v_lshlrev_b32_e32 v255, 2, v255
	ds_bpermute_b32 v239, v255, v134
	ds_bpermute_b32 v253, v255, v135
	s_waitcnt lgkmcnt(0)
	v_cmp_gt_u32_e32 vcc, 16, v254
	s_nop 1
	v_cndmask_b32_e32 v236, v253, v239, vcc
	v_cmp_gt_u32_e32 vcc, 32, v254
	s_nop 1
	v_cndmask_b32_e32 v236, 0, v236, vcc
	ds_bpermute_b32 v239, v255, v138
	ds_bpermute_b32 v253, v255, v139
	s_waitcnt lgkmcnt(0)
	v_cmp_gt_u32_e32 vcc, 16, v254
	s_nop 1
	v_cndmask_b32_e32 v207, v253, v239, vcc
	v_cmp_gt_u32_e32 vcc, 32, v254
	s_nop 1
	v_cndmask_b32_e32 v207, 0, v207, vcc
	s_branch .LBB0_663
	s_nop 0

; __global__ void __launch_bounds__(NTHREADS, 2) mega_kernel(Params p) {
	.amdhsa_kernel _Z11mega_kernel6Params
		.amdhsa_group_segment_fixed_size 0
		.amdhsa_private_segment_fixed_size 0
		.amdhsa_kernarg_size 528
		.amdhsa_user_sgpr_count 2
		.amdhsa_user_sgpr_dispatch_ptr 0
		.amdhsa_user_sgpr_queue_ptr 0
		.amdhsa_user_sgpr_kernarg_segment_ptr 1
		.amdhsa_user_sgpr_dispatch_id 0
		.amdhsa_user_sgpr_kernarg_preload_length 0
		.amdhsa_user_sgpr_kernarg_preload_offset 0
		.amdhsa_user_sgpr_private_segment_size 0
		.amdhsa_uses_dynamic_stack 0
		.amdhsa_enable_private_segment 0
		.amdhsa_system_sgpr_workgroup_id_x 1
		.amdhsa_system_sgpr_workgroup_id_y 0
		.amdhsa_system_sgpr_workgroup_id_z 0
		.amdhsa_system_sgpr_workgroup_info 0
		.amdhsa_system_vgpr_workitem_id 2
		.amdhsa_next_free_vgpr 256
		.amdhsa_next_free_sgpr 102
		.amdhsa_accum_offset 256
		.amdhsa_reserve_vcc 1
		.amdhsa_float_round_mode_32 0
		.amdhsa_float_round_mode_16_64 0
		.amdhsa_float_denorm_mode_32 3
		.amdhsa_float_denorm_mode_16_64 3
		.amdhsa_dx10_clamp 1
		.amdhsa_ieee_mode 1
		.amdhsa_fp16_overflow 0
		.amdhsa_tg_split 0
		.amdhsa_exception_fp_ieee_invalid_op 0
		.amdhsa_exception_fp_denorm_src 0
		.amdhsa_exception_fp_ieee_div_zero 0
		.amdhsa_exception_fp_ieee_overflow 0
		.amdhsa_exception_fp_ieee_underflow 0
		.amdhsa_exception_fp_ieee_inexact 0
		.amdhsa_exception_int_div_zero 0
	.end_amdhsa_kernel

; __global__ void __launch_bounds__(NTHREADS, 2) mega_kernel(Params p) {
amdhsa.kernels:
  - .agpr_count:     0
    .args:
      - .offset:         0
        .size:           272
        .value_kind:     by_value
      - .offset:         272
        .size:           4
        .value_kind:     hidden_block_count_x
      - .offset:         276
        .size:           4
        .value_kind:     hidden_block_count_y
      - .offset:         280
        .size:           4
        .value_kind:     hidden_block_count_z
      - .offset:         284
        .size:           2
        .value_kind:     hidden_group_size_x
      - .offset:         286
        .size:           2
        .value_kind:     hidden_group_size_y
      - .offset:         288
        .size:           2
        .value_kind:     hidden_group_size_z
      - .offset:         290
        .size:           2
        .value_kind:     hidden_remainder_x
      - .offset:         292
        .size:           2
        .value_kind:     hidden_remainder_y
      - .offset:         294
        .size:           2
        .value_kind:     hidden_remainder_z
      - .offset:         312
        .size:           8
        .value_kind:     hidden_global_offset_x
      - .offset:         320
        .size:           8
        .value_kind:     hidden_global_offset_y
      - .offset:         328
        .size:           8
        .value_kind:     hidden_global_offset_z
      - .offset:         336
        .size:           2
        .value_kind:     hidden_grid_dims
      - .offset:         360
        .size:           8
        .value_kind:     hidden_multigrid_sync_arg
      - .offset:         392
        .size:           4
        .value_kind:     hidden_dynamic_lds_size
    .group_segment_fixed_size: 0
    .kernarg_segment_align: 8
    .kernarg_segment_size: 528
    .language:       OpenCL C
    .language_version:
      - 2
      - 0
    .max_flat_workgroup_size: 256
    .name:           _Z11mega_kernel6Params
    .private_segment_fixed_size: 0
    .sgpr_count:     108
    .sgpr_spill_count: 285
    .symbol:         _Z11mega_kernel6Params.kd
    .uniform_work_group_size: 1
    .uses_dynamic_stack: false
    .vgpr_count:     256
    .vgpr_spill_count: 0
    .wavefront_size: 64
